# K-loops: set-up instructions between a phase's last MFMA and its closing barrier moved behind the barrier; loop counter/exit test rotated out of the last MFMA segment
# speedup vs baseline: 1.0031x; 1.0031x over previous
.Lpeel_p1:
	ds_read_b128 v[130:133], v173
	ds_read_b128 v[134:137], v173 offset:1024
	ds_read_b128 v[138:141], v173 offset:2048
	ds_read_b128 v[142:145], v173 offset:3072
	s_add_u32 s6, s2, 0xfffc0080
	s_addc_u32 s7, s3, -1
	s_cmp_eq_u32 s73, 12
	s_cselect_b32 s9, s1, s7
	s_cselect_b32 s8, s33, s6
	s_cselect_b32 s7, s39, s72
	s_cselect_b32 s6, s41, s71
	s_add_i32 m0, s50, 0xc000
	ds_read_b128 v[180:183], v175
	ds_read_b128 v[184:187], v175 offset:1024
	ds_read_b128 v[190:193], v175 offset:2048
	ds_read_b128 v[194:197], v175 offset:3072
	ds_read_b128 v[198:201], v175 offset:4096
	ds_read_b128 v[202:205], v175 offset:5120
	ds_read_b128 v[206:209], v175 offset:6144
	ds_read_b128 v[210:213], v175 offset:7168
	global_load_lds_dwordx4 v156, s[2:3]
	s_add_i32 m0, s50, 0xe000
	s_nop 0
	global_load_lds_dwordx4 v158, s[2:3]
	s_waitcnt lgkmcnt(8)
	s_barrier
	s_waitcnt lgkmcnt(0)
	v_mfma_f32_16x16x32_bf16 v[126:129], v[130:133], v[180:183], 0
	v_mfma_f32_16x16x32_bf16 v[122:125], v[138:141], v[180:183], 0
	v_mfma_f32_16x16x32_bf16 v[118:121], v[130:133], v[190:193], 0
	v_mfma_f32_16x16x32_bf16 v[110:113], v[138:141], v[190:193], 0
	v_mfma_f32_16x16x32_bf16 v[102:105], v[130:133], v[198:201], 0
	v_mfma_f32_16x16x32_bf16 v[94:97], v[138:141], v[198:201], 0
	v_mfma_f32_16x16x32_bf16 v[86:89], v[130:133], v[206:209], 0
	v_mfma_f32_16x16x32_bf16 v[78:81], v[138:141], v[206:209], 0
	v_mfma_f32_16x16x32_bf16 v[126:129], v[134:137], v[184:187], v[126:129]
	v_mfma_f32_16x16x32_bf16 v[122:125], v[142:145], v[184:187], v[122:125]
	v_mfma_f32_16x16x32_bf16 v[118:121], v[134:137], v[194:197], v[118:121]
	v_mfma_f32_16x16x32_bf16 v[110:113], v[142:145], v[194:197], v[110:113]
	v_mfma_f32_16x16x32_bf16 v[102:105], v[134:137], v[202:205], v[102:105]
	v_mfma_f32_16x16x32_bf16 v[94:97], v[142:145], v[202:205], v[94:97]
	v_mfma_f32_16x16x32_bf16 v[86:89], v[134:137], v[210:213], v[86:89]
	v_mfma_f32_16x16x32_bf16 v[78:81], v[142:145], v[210:213], v[78:81]
	s_barrier
	s_add_i32 s74, s66, s49
	s_add_u32 s98, s6, 0x80
	s_addc_u32 s99, s7, 0
	s_mov_b32 m0, s74
	ds_read_b128 v[214:217], v177
	ds_read_b128 v[218:221], v177 offset:1024
	ds_read_b128 v[222:225], v177 offset:2048
	ds_read_b128 v[226:229], v177 offset:3072
	global_load_lds_dwordx4 v148, s[6:7]
	s_add_i32 m0, s74, 0x2000
	s_nop 0
	global_load_lds_dwordx4 v152, s[6:7]
	s_barrier
	s_waitcnt lgkmcnt(0)
	v_mfma_f32_16x16x32_bf16 v[114:117], v[214:217], v[180:183], 0
	v_mfma_f32_16x16x32_bf16 v[106:109], v[222:225], v[180:183], 0
	v_mfma_f32_16x16x32_bf16 v[98:101], v[214:217], v[190:193], 0
	v_mfma_f32_16x16x32_bf16 v[90:93], v[222:225], v[190:193], 0
	v_mfma_f32_16x16x32_bf16 v[82:85], v[214:217], v[198:201], 0
	v_mfma_f32_16x16x32_bf16 v[74:77], v[222:225], v[198:201], 0
	v_mfma_f32_16x16x32_bf16 v[70:73], v[214:217], v[206:209], 0
	v_mfma_f32_16x16x32_bf16 v[66:69], v[222:225], v[206:209], 0
	v_mfma_f32_16x16x32_bf16 v[114:117], v[218:221], v[184:187], v[114:117]
	v_mfma_f32_16x16x32_bf16 v[106:109], v[226:229], v[184:187], v[106:109]
	v_mfma_f32_16x16x32_bf16 v[98:101], v[218:221], v[194:197], v[98:101]
	v_mfma_f32_16x16x32_bf16 v[90:93], v[226:229], v[194:197], v[90:93]
	v_mfma_f32_16x16x32_bf16 v[82:85], v[218:221], v[202:205], v[82:85]
	v_mfma_f32_16x16x32_bf16 v[74:77], v[226:229], v[202:205], v[74:77]
	v_mfma_f32_16x16x32_bf16 v[70:73], v[218:221], v[210:213], v[70:73]
	v_mfma_f32_16x16x32_bf16 v[66:69], v[226:229], v[210:213], v[66:69]
	s_barrier
	s_mov_b32 m0, s50
	s_add_u32 s100, s8, 0x80
	s_addc_u32 s101, s9, 0
	ds_read_b128 v[180:183], v175 offset:16384
	ds_read_b128 v[184:187], v175 offset:17408
	ds_read_b128 v[190:193], v175 offset:18432
	ds_read_b128 v[194:197], v175 offset:19456
	ds_read_b128 v[198:201], v175 offset:20480
	ds_read_b128 v[202:205], v175 offset:21504
	ds_read_b128 v[206:209], v175 offset:22528
	ds_read_b128 v[210:213], v175 offset:23552
	global_load_lds_dwordx4 v146, s[8:9]
	s_mov_b32 m0, s51
	s_nop 0
	global_load_lds_dwordx4 v150, s[8:9]
	s_barrier
	s_waitcnt lgkmcnt(0)
	v_mfma_f32_16x16x32_bf16 v[62:65], v[130:133], v[180:183], 0
	v_mfma_f32_16x16x32_bf16 v[58:61], v[138:141], v[180:183], 0
	v_mfma_f32_16x16x32_bf16 v[54:57], v[130:133], v[190:193], 0
	v_mfma_f32_16x16x32_bf16 v[46:49], v[138:141], v[190:193], 0
	v_mfma_f32_16x16x32_bf16 v[38:41], v[130:133], v[198:201], 0
	v_mfma_f32_16x16x32_bf16 v[30:33], v[138:141], v[198:201], 0
	v_mfma_f32_16x16x32_bf16 v[22:25], v[130:133], v[206:209], 0
	v_mfma_f32_16x16x32_bf16 v[14:17], v[138:141], v[206:209], 0
	v_mfma_f32_16x16x32_bf16 v[62:65], v[134:137], v[184:187], v[62:65]
	v_mfma_f32_16x16x32_bf16 v[58:61], v[142:145], v[184:187], v[58:61]
	v_mfma_f32_16x16x32_bf16 v[54:57], v[134:137], v[194:197], v[54:57]
	v_mfma_f32_16x16x32_bf16 v[46:49], v[142:145], v[194:197], v[46:49]
	v_mfma_f32_16x16x32_bf16 v[38:41], v[134:137], v[202:205], v[38:41]
	v_mfma_f32_16x16x32_bf16 v[30:33], v[142:145], v[202:205], v[30:33]
	v_mfma_f32_16x16x32_bf16 v[22:25], v[134:137], v[210:213], v[22:25]
	v_mfma_f32_16x16x32_bf16 v[14:17], v[142:145], v[210:213], v[14:17]
	s_barrier
	s_add_u32 s74, s6, 0x40000
	s_addc_u32 s75, s7, 0
	s_add_i32 s76, s67, s49
	s_mov_b32 m0, s76
	s_nop 0
	global_load_lds_dwordx4 v148, s[74:75]
	s_add_i32 m0, s76, 0x2000
	s_nop 0
	global_load_lds_dwordx4 v152, s[74:75]
	s_waitcnt vmcnt(6)
	s_barrier
	v_mfma_f32_16x16x32_bf16 v[50:53], v[214:217], v[180:183], 0
	v_mfma_f32_16x16x32_bf16 v[42:45], v[222:225], v[180:183], 0
	v_mfma_f32_16x16x32_bf16 v[34:37], v[214:217], v[190:193], 0
	v_mfma_f32_16x16x32_bf16 v[26:29], v[222:225], v[190:193], 0
	v_mfma_f32_16x16x32_bf16 v[18:21], v[214:217], v[198:201], 0
	v_mfma_f32_16x16x32_bf16 v[10:13], v[222:225], v[198:201], 0
	v_mfma_f32_16x16x32_bf16 v[6:9], v[214:217], v[206:209], 0
	v_mfma_f32_16x16x32_bf16 v[2:5], v[222:225], v[206:209], 0
	v_mfma_f32_16x16x32_bf16 v[50:53], v[218:221], v[184:187], v[50:53]
	v_mfma_f32_16x16x32_bf16 v[42:45], v[226:229], v[184:187], v[42:45]
	v_mfma_f32_16x16x32_bf16 v[34:37], v[218:221], v[194:197], v[34:37]
	v_mfma_f32_16x16x32_bf16 v[26:29], v[226:229], v[194:197], v[26:29]
	v_mfma_f32_16x16x32_bf16 v[18:21], v[218:221], v[202:205], v[18:21]
	v_mfma_f32_16x16x32_bf16 v[10:13], v[226:229], v[202:205], v[10:13]
	v_mfma_f32_16x16x32_bf16 v[6:9], v[218:221], v[210:213], v[6:9]
	v_mfma_f32_16x16x32_bf16 v[2:5], v[226:229], v[210:213], v[2:5]
	s_barrier
	s_add_i32 s74, 0, 0x18000
	v_add_u32_e32 v142, s74, v171
	ds_read_b128 v[130:133], v142
	ds_read_b128 v[134:137], v142 offset:1024
	ds_read_b128 v[138:141], v142 offset:2048
	ds_read_b128 v[142:145], v142 offset:3072
	s_add_u32 s8, s8, 0x40000
	s_addc_u32 s9, s9, 0
	s_mov_b32 m0, s52
	ds_read_b128 v[180:183], v175 offset:32768
	ds_read_b128 v[184:187], v175 offset:33792
	ds_read_b128 v[190:193], v175 offset:34816
	ds_read_b128 v[194:197], v175 offset:35840
	ds_read_b128 v[198:201], v175 offset:36864
	ds_read_b128 v[202:205], v175 offset:37888
	ds_read_b128 v[206:209], v175 offset:38912
	ds_read_b128 v[210:213], v175 offset:39936
	global_load_lds_dwordx4 v146, s[8:9]
	s_mov_b32 m0, s53
	s_nop 0
	global_load_lds_dwordx4 v150, s[8:9]
	s_waitcnt lgkmcnt(8)
	s_barrier
	s_waitcnt lgkmcnt(0)
	v_mfma_f32_16x16x32_bf16 v[126:129], v[130:133], v[180:183], v[126:129]
	v_mfma_f32_16x16x32_bf16 v[122:125], v[138:141], v[180:183], v[122:125]
	v_mfma_f32_16x16x32_bf16 v[118:121], v[130:133], v[190:193], v[118:121]
	v_mfma_f32_16x16x32_bf16 v[110:113], v[138:141], v[190:193], v[110:113]
	v_mfma_f32_16x16x32_bf16 v[102:105], v[130:133], v[198:201], v[102:105]
	v_mfma_f32_16x16x32_bf16 v[94:97], v[138:141], v[198:201], v[94:97]
	v_mfma_f32_16x16x32_bf16 v[86:89], v[130:133], v[206:209], v[86:89]
	v_mfma_f32_16x16x32_bf16 v[78:81], v[138:141], v[206:209], v[78:81]
	v_mfma_f32_16x16x32_bf16 v[126:129], v[134:137], v[184:187], v[126:129]
	v_mfma_f32_16x16x32_bf16 v[122:125], v[142:145], v[184:187], v[122:125]
	v_mfma_f32_16x16x32_bf16 v[118:121], v[134:137], v[194:197], v[118:121]
	v_mfma_f32_16x16x32_bf16 v[110:113], v[142:145], v[194:197], v[110:113]
	v_mfma_f32_16x16x32_bf16 v[102:105], v[134:137], v[202:205], v[102:105]
	v_mfma_f32_16x16x32_bf16 v[94:97], v[142:145], v[202:205], v[94:97]
	v_mfma_f32_16x16x32_bf16 v[86:89], v[134:137], v[210:213], v[86:89]
	v_mfma_f32_16x16x32_bf16 v[78:81], v[142:145], v[210:213], v[78:81]
	s_barrier
	s_add_i32 s8, 0, 0x1c000
	s_add_i32 s9, s74, s49
	v_add_u32_e32 v154, s8, v171
	s_mov_b32 m0, s9
	ds_read_b128 v[214:217], v154
	ds_read_b128 v[218:221], v154 offset:1024
	ds_read_b128 v[222:225], v154 offset:2048
	ds_read_b128 v[226:229], v154 offset:3072
	global_load_lds_dwordx4 v148, s[98:99]
	s_add_i32 m0, s9, 0x2000
	s_nop 0
	global_load_lds_dwordx4 v152, s[98:99]
	s_barrier
	s_waitcnt lgkmcnt(0)
	v_mfma_f32_16x16x32_bf16 v[114:117], v[214:217], v[180:183], v[114:117]
	v_mfma_f32_16x16x32_bf16 v[106:109], v[222:225], v[180:183], v[106:109]
	v_mfma_f32_16x16x32_bf16 v[98:101], v[214:217], v[190:193], v[98:101]
	v_mfma_f32_16x16x32_bf16 v[90:93], v[222:225], v[190:193], v[90:93]
	v_mfma_f32_16x16x32_bf16 v[82:85], v[214:217], v[198:201], v[82:85]
	v_mfma_f32_16x16x32_bf16 v[74:77], v[222:225], v[198:201], v[74:77]
	v_mfma_f32_16x16x32_bf16 v[70:73], v[214:217], v[206:209], v[70:73]
	v_mfma_f32_16x16x32_bf16 v[66:69], v[222:225], v[206:209], v[66:69]
	v_mfma_f32_16x16x32_bf16 v[114:117], v[218:221], v[184:187], v[114:117]
	v_mfma_f32_16x16x32_bf16 v[106:109], v[226:229], v[184:187], v[106:109]
	v_mfma_f32_16x16x32_bf16 v[98:101], v[218:221], v[194:197], v[98:101]
	v_mfma_f32_16x16x32_bf16 v[90:93], v[226:229], v[194:197], v[90:93]
	v_mfma_f32_16x16x32_bf16 v[82:85], v[218:221], v[202:205], v[82:85]
	v_mfma_f32_16x16x32_bf16 v[74:77], v[226:229], v[202:205], v[74:77]
	v_mfma_f32_16x16x32_bf16 v[70:73], v[218:221], v[210:213], v[70:73]
	v_mfma_f32_16x16x32_bf16 v[66:69], v[226:229], v[210:213], v[66:69]
	s_barrier
	s_mov_b32 m0, s56
	ds_read_b128 v[180:183], v175 offset:49152
	ds_read_b128 v[184:187], v175 offset:50176
	ds_read_b128 v[190:193], v175 offset:51200
	ds_read_b128 v[194:197], v175 offset:52224
	ds_read_b128 v[198:201], v175 offset:53248
	ds_read_b128 v[202:205], v175 offset:54272
	ds_read_b128 v[206:209], v175 offset:55296
	ds_read_b128 v[210:213], v175 offset:56320
	global_load_lds_dwordx4 v146, s[100:101]
	s_mov_b32 m0, s57
	s_nop 0
	global_load_lds_dwordx4 v150, s[100:101]
	s_barrier
	s_waitcnt lgkmcnt(0)
	v_mfma_f32_16x16x32_bf16 v[62:65], v[130:133], v[180:183], v[62:65]
	v_mfma_f32_16x16x32_bf16 v[58:61], v[138:141], v[180:183], v[58:61]
	v_mfma_f32_16x16x32_bf16 v[54:57], v[130:133], v[190:193], v[54:57]
	v_mfma_f32_16x16x32_bf16 v[46:49], v[138:141], v[190:193], v[46:49]
	v_mfma_f32_16x16x32_bf16 v[38:41], v[130:133], v[198:201], v[38:41]
	v_mfma_f32_16x16x32_bf16 v[30:33], v[138:141], v[198:201], v[30:33]
	v_mfma_f32_16x16x32_bf16 v[22:25], v[130:133], v[206:209], v[22:25]
	v_mfma_f32_16x16x32_bf16 v[14:17], v[138:141], v[206:209], v[14:17]
	v_mfma_f32_16x16x32_bf16 v[62:65], v[134:137], v[184:187], v[62:65]
	v_mfma_f32_16x16x32_bf16 v[58:61], v[142:145], v[184:187], v[58:61]
	v_mfma_f32_16x16x32_bf16 v[54:57], v[134:137], v[194:197], v[54:57]
	v_mfma_f32_16x16x32_bf16 v[46:49], v[142:145], v[194:197], v[46:49]
	v_mfma_f32_16x16x32_bf16 v[38:41], v[134:137], v[202:205], v[38:41]
	v_mfma_f32_16x16x32_bf16 v[30:33], v[142:145], v[202:205], v[30:33]
	v_mfma_f32_16x16x32_bf16 v[22:25], v[134:137], v[210:213], v[22:25]
	v_mfma_f32_16x16x32_bf16 v[14:17], v[142:145], v[210:213], v[14:17]
	s_barrier
	s_add_u32 s6, s6, 0x40080
	s_addc_u32 s7, s7, 0
	s_add_i32 s8, s8, s49
	s_mov_b32 m0, s8
	s_nop 0
	global_load_lds_dwordx4 v148, s[6:7]
	s_add_i32 m0, s8, 0x2000
	s_nop 0
	global_load_lds_dwordx4 v152, s[6:7]
	s_add_i32 s73, s73, 2
	s_add_u32 s2, s2, 0x100
	s_addc_u32 s3, s3, 0
	s_add_u32 s71, s71, 0x100
	s_addc_u32 s72, s72, 0
	s_cmp_gt_u32 s73, 13
	s_waitcnt vmcnt(6)
	s_barrier
	v_mfma_f32_16x16x32_bf16 v[50:53], v[214:217], v[180:183], v[50:53]
	v_mfma_f32_16x16x32_bf16 v[42:45], v[222:225], v[180:183], v[42:45]
	v_mfma_f32_16x16x32_bf16 v[34:37], v[214:217], v[190:193], v[34:37]
	v_mfma_f32_16x16x32_bf16 v[26:29], v[222:225], v[190:193], v[26:29]
	v_mfma_f32_16x16x32_bf16 v[18:21], v[214:217], v[198:201], v[18:21]
	v_mfma_f32_16x16x32_bf16 v[10:13], v[222:225], v[198:201], v[10:13]
	v_mfma_f32_16x16x32_bf16 v[6:9], v[214:217], v[206:209], v[6:9]
	v_mfma_f32_16x16x32_bf16 v[2:5], v[222:225], v[206:209], v[2:5]
	v_mfma_f32_16x16x32_bf16 v[50:53], v[218:221], v[184:187], v[50:53]
	v_mfma_f32_16x16x32_bf16 v[42:45], v[226:229], v[184:187], v[42:45]
	v_mfma_f32_16x16x32_bf16 v[34:37], v[218:221], v[194:197], v[34:37]
	v_mfma_f32_16x16x32_bf16 v[26:29], v[226:229], v[194:197], v[26:29]
	v_mfma_f32_16x16x32_bf16 v[18:21], v[218:221], v[202:205], v[18:21]
	v_mfma_f32_16x16x32_bf16 v[10:13], v[226:229], v[202:205], v[10:13]
	v_mfma_f32_16x16x32_bf16 v[6:9], v[218:221], v[210:213], v[6:9]
	v_mfma_f32_16x16x32_bf16 v[2:5], v[226:229], v[210:213], v[2:5]
	s_barrier
	s_cbranch_scc1 .Lpeel_p1_exit
.LBB0_212:
	ds_read_b128 v[130:133], v173
	ds_read_b128 v[134:137], v173 offset:1024
	ds_read_b128 v[138:141], v173 offset:2048
	ds_read_b128 v[142:145], v173 offset:3072
	s_add_u32 s6, s2, 0xfffc0080
	s_addc_u32 s7, s3, -1
	s_cmp_eq_u32 s73, 12
	s_cselect_b32 s9, s1, s7
	s_cselect_b32 s8, s33, s6
	s_cselect_b32 s7, s39, s72
	s_cselect_b32 s6, s41, s71
	s_add_i32 m0, s50, 0xc000
	ds_read_b128 v[180:183], v175
	ds_read_b128 v[184:187], v175 offset:1024
	ds_read_b128 v[190:193], v175 offset:2048
	ds_read_b128 v[194:197], v175 offset:3072
	ds_read_b128 v[198:201], v175 offset:4096
	ds_read_b128 v[202:205], v175 offset:5120
	ds_read_b128 v[206:209], v175 offset:6144
	ds_read_b128 v[210:213], v175 offset:7168
	global_load_lds_dwordx4 v156, s[2:3]
	s_add_i32 m0, s50, 0xe000
	s_nop 0
	global_load_lds_dwordx4 v158, s[2:3]
	s_waitcnt lgkmcnt(8)
	s_barrier
	s_waitcnt lgkmcnt(0)
	v_mfma_f32_16x16x32_bf16 v[126:129], v[130:133], v[180:183], v[126:129]
	v_mfma_f32_16x16x32_bf16 v[122:125], v[138:141], v[180:183], v[122:125]
	v_mfma_f32_16x16x32_bf16 v[118:121], v[130:133], v[190:193], v[118:121]
	v_mfma_f32_16x16x32_bf16 v[110:113], v[138:141], v[190:193], v[110:113]
	v_mfma_f32_16x16x32_bf16 v[102:105], v[130:133], v[198:201], v[102:105]
	v_mfma_f32_16x16x32_bf16 v[94:97], v[138:141], v[198:201], v[94:97]
	v_mfma_f32_16x16x32_bf16 v[86:89], v[130:133], v[206:209], v[86:89]
	v_mfma_f32_16x16x32_bf16 v[78:81], v[138:141], v[206:209], v[78:81]
	v_mfma_f32_16x16x32_bf16 v[126:129], v[134:137], v[184:187], v[126:129]
	v_mfma_f32_16x16x32_bf16 v[122:125], v[142:145], v[184:187], v[122:125]
	v_mfma_f32_16x16x32_bf16 v[118:121], v[134:137], v[194:197], v[118:121]
	v_mfma_f32_16x16x32_bf16 v[110:113], v[142:145], v[194:197], v[110:113]
	v_mfma_f32_16x16x32_bf16 v[102:105], v[134:137], v[202:205], v[102:105]
	v_mfma_f32_16x16x32_bf16 v[94:97], v[142:145], v[202:205], v[94:97]
	v_mfma_f32_16x16x32_bf16 v[86:89], v[134:137], v[210:213], v[86:89]
	v_mfma_f32_16x16x32_bf16 v[78:81], v[142:145], v[210:213], v[78:81]
	s_barrier
	s_add_i32 s74, s66, s49
	s_add_u32 s98, s6, 0x80
	s_addc_u32 s99, s7, 0
	s_mov_b32 m0, s74
	ds_read_b128 v[214:217], v177
	ds_read_b128 v[218:221], v177 offset:1024
	ds_read_b128 v[222:225], v177 offset:2048
	ds_read_b128 v[226:229], v177 offset:3072
	global_load_lds_dwordx4 v148, s[6:7]
	s_add_i32 m0, s74, 0x2000
	s_nop 0
	global_load_lds_dwordx4 v152, s[6:7]
	s_barrier
	s_waitcnt lgkmcnt(0)
	v_mfma_f32_16x16x32_bf16 v[114:117], v[214:217], v[180:183], v[114:117]
	v_mfma_f32_16x16x32_bf16 v[106:109], v[222:225], v[180:183], v[106:109]
	v_mfma_f32_16x16x32_bf16 v[98:101], v[214:217], v[190:193], v[98:101]
	v_mfma_f32_16x16x32_bf16 v[90:93], v[222:225], v[190:193], v[90:93]
	v_mfma_f32_16x16x32_bf16 v[82:85], v[214:217], v[198:201], v[82:85]
	v_mfma_f32_16x16x32_bf16 v[74:77], v[222:225], v[198:201], v[74:77]
	v_mfma_f32_16x16x32_bf16 v[70:73], v[214:217], v[206:209], v[70:73]
	v_mfma_f32_16x16x32_bf16 v[66:69], v[222:225], v[206:209], v[66:69]
	v_mfma_f32_16x16x32_bf16 v[114:117], v[218:221], v[184:187], v[114:117]
	v_mfma_f32_16x16x32_bf16 v[106:109], v[226:229], v[184:187], v[106:109]
	v_mfma_f32_16x16x32_bf16 v[98:101], v[218:221], v[194:197], v[98:101]
	v_mfma_f32_16x16x32_bf16 v[90:93], v[226:229], v[194:197], v[90:93]
	v_mfma_f32_16x16x32_bf16 v[82:85], v[218:221], v[202:205], v[82:85]
	v_mfma_f32_16x16x32_bf16 v[74:77], v[226:229], v[202:205], v[74:77]
	v_mfma_f32_16x16x32_bf16 v[70:73], v[218:221], v[210:213], v[70:73]
	v_mfma_f32_16x16x32_bf16 v[66:69], v[226:229], v[210:213], v[66:69]
	s_barrier
	s_mov_b32 m0, s50
	s_add_u32 s100, s8, 0x80
	s_addc_u32 s101, s9, 0
	ds_read_b128 v[180:183], v175 offset:16384
	ds_read_b128 v[184:187], v175 offset:17408
	ds_read_b128 v[190:193], v175 offset:18432
	ds_read_b128 v[194:197], v175 offset:19456
	ds_read_b128 v[198:201], v175 offset:20480
	ds_read_b128 v[202:205], v175 offset:21504
	ds_read_b128 v[206:209], v175 offset:22528
	ds_read_b128 v[210:213], v175 offset:23552
	global_load_lds_dwordx4 v146, s[8:9]
	s_mov_b32 m0, s51
	s_nop 0
	global_load_lds_dwordx4 v150, s[8:9]
	s_barrier
	s_waitcnt lgkmcnt(0)
	v_mfma_f32_16x16x32_bf16 v[62:65], v[130:133], v[180:183], v[62:65]
	v_mfma_f32_16x16x32_bf16 v[58:61], v[138:141], v[180:183], v[58:61]
	v_mfma_f32_16x16x32_bf16 v[54:57], v[130:133], v[190:193], v[54:57]
	v_mfma_f32_16x16x32_bf16 v[46:49], v[138:141], v[190:193], v[46:49]
	v_mfma_f32_16x16x32_bf16 v[38:41], v[130:133], v[198:201], v[38:41]
	v_mfma_f32_16x16x32_bf16 v[30:33], v[138:141], v[198:201], v[30:33]
	v_mfma_f32_16x16x32_bf16 v[22:25], v[130:133], v[206:209], v[22:25]
	v_mfma_f32_16x16x32_bf16 v[14:17], v[138:141], v[206:209], v[14:17]
	v_mfma_f32_16x16x32_bf16 v[62:65], v[134:137], v[184:187], v[62:65]
	v_mfma_f32_16x16x32_bf16 v[58:61], v[142:145], v[184:187], v[58:61]
	v_mfma_f32_16x16x32_bf16 v[54:57], v[134:137], v[194:197], v[54:57]
	v_mfma_f32_16x16x32_bf16 v[46:49], v[142:145], v[194:197], v[46:49]
	v_mfma_f32_16x16x32_bf16 v[38:41], v[134:137], v[202:205], v[38:41]
	v_mfma_f32_16x16x32_bf16 v[30:33], v[142:145], v[202:205], v[30:33]
	v_mfma_f32_16x16x32_bf16 v[22:25], v[134:137], v[210:213], v[22:25]
	v_mfma_f32_16x16x32_bf16 v[14:17], v[142:145], v[210:213], v[14:17]
	s_barrier
	s_add_u32 s74, s6, 0x40000
	s_addc_u32 s75, s7, 0
	s_add_i32 s76, s67, s49
	s_mov_b32 m0, s76
	s_nop 0
	global_load_lds_dwordx4 v148, s[74:75]
	s_add_i32 m0, s76, 0x2000
	s_nop 0
	global_load_lds_dwordx4 v152, s[74:75]
	s_waitcnt vmcnt(6)
	s_barrier
	v_mfma_f32_16x16x32_bf16 v[50:53], v[214:217], v[180:183], v[50:53]
	v_mfma_f32_16x16x32_bf16 v[42:45], v[222:225], v[180:183], v[42:45]
	v_mfma_f32_16x16x32_bf16 v[34:37], v[214:217], v[190:193], v[34:37]
	v_mfma_f32_16x16x32_bf16 v[26:29], v[222:225], v[190:193], v[26:29]
	v_mfma_f32_16x16x32_bf16 v[18:21], v[214:217], v[198:201], v[18:21]
	v_mfma_f32_16x16x32_bf16 v[10:13], v[222:225], v[198:201], v[10:13]
	v_mfma_f32_16x16x32_bf16 v[6:9], v[214:217], v[206:209], v[6:9]
	v_mfma_f32_16x16x32_bf16 v[2:5], v[222:225], v[206:209], v[2:5]
	v_mfma_f32_16x16x32_bf16 v[50:53], v[218:221], v[184:187], v[50:53]
	v_mfma_f32_16x16x32_bf16 v[42:45], v[226:229], v[184:187], v[42:45]
	v_mfma_f32_16x16x32_bf16 v[34:37], v[218:221], v[194:197], v[34:37]
	v_mfma_f32_16x16x32_bf16 v[26:29], v[226:229], v[194:197], v[26:29]
	v_mfma_f32_16x16x32_bf16 v[18:21], v[218:221], v[202:205], v[18:21]
	v_mfma_f32_16x16x32_bf16 v[10:13], v[226:229], v[202:205], v[10:13]
	v_mfma_f32_16x16x32_bf16 v[6:9], v[218:221], v[210:213], v[6:9]
	v_mfma_f32_16x16x32_bf16 v[2:5], v[226:229], v[210:213], v[2:5]
	s_barrier
	s_add_i32 s74, 0, 0x18000
	v_add_u32_e32 v142, s74, v171
	ds_read_b128 v[130:133], v142
	ds_read_b128 v[134:137], v142 offset:1024
	ds_read_b128 v[138:141], v142 offset:2048
	ds_read_b128 v[142:145], v142 offset:3072
	s_add_u32 s8, s8, 0x40000
	s_addc_u32 s9, s9, 0
	s_mov_b32 m0, s52
	ds_read_b128 v[180:183], v175 offset:32768
	ds_read_b128 v[184:187], v175 offset:33792
	ds_read_b128 v[190:193], v175 offset:34816
	ds_read_b128 v[194:197], v175 offset:35840
	ds_read_b128 v[198:201], v175 offset:36864
	ds_read_b128 v[202:205], v175 offset:37888
	ds_read_b128 v[206:209], v175 offset:38912
	ds_read_b128 v[210:213], v175 offset:39936
	global_load_lds_dwordx4 v146, s[8:9]
	s_mov_b32 m0, s53
	s_nop 0
	global_load_lds_dwordx4 v150, s[8:9]
	s_waitcnt lgkmcnt(8)
	s_barrier
	s_waitcnt lgkmcnt(0)
	v_mfma_f32_16x16x32_bf16 v[126:129], v[130:133], v[180:183], v[126:129]
	v_mfma_f32_16x16x32_bf16 v[122:125], v[138:141], v[180:183], v[122:125]
	v_mfma_f32_16x16x32_bf16 v[118:121], v[130:133], v[190:193], v[118:121]
	v_mfma_f32_16x16x32_bf16 v[110:113], v[138:141], v[190:193], v[110:113]
	v_mfma_f32_16x16x32_bf16 v[102:105], v[130:133], v[198:201], v[102:105]
	v_mfma_f32_16x16x32_bf16 v[94:97], v[138:141], v[198:201], v[94:97]
	v_mfma_f32_16x16x32_bf16 v[86:89], v[130:133], v[206:209], v[86:89]
	v_mfma_f32_16x16x32_bf16 v[78:81], v[138:141], v[206:209], v[78:81]
	v_mfma_f32_16x16x32_bf16 v[126:129], v[134:137], v[184:187], v[126:129]
	v_mfma_f32_16x16x32_bf16 v[122:125], v[142:145], v[184:187], v[122:125]
	v_mfma_f32_16x16x32_bf16 v[118:121], v[134:137], v[194:197], v[118:121]
	v_mfma_f32_16x16x32_bf16 v[110:113], v[142:145], v[194:197], v[110:113]
	v_mfma_f32_16x16x32_bf16 v[102:105], v[134:137], v[202:205], v[102:105]
	v_mfma_f32_16x16x32_bf16 v[94:97], v[142:145], v[202:205], v[94:97]
	v_mfma_f32_16x16x32_bf16 v[86:89], v[134:137], v[210:213], v[86:89]
	v_mfma_f32_16x16x32_bf16 v[78:81], v[142:145], v[210:213], v[78:81]
	s_barrier
	s_add_i32 s8, 0, 0x1c000
	s_add_i32 s9, s74, s49
	v_add_u32_e32 v154, s8, v171
	s_mov_b32 m0, s9
	ds_read_b128 v[214:217], v154
	ds_read_b128 v[218:221], v154 offset:1024
	ds_read_b128 v[222:225], v154 offset:2048
	ds_read_b128 v[226:229], v154 offset:3072
	global_load_lds_dwordx4 v148, s[98:99]
	s_add_i32 m0, s9, 0x2000
	s_nop 0
	global_load_lds_dwordx4 v152, s[98:99]
	s_barrier
	s_waitcnt lgkmcnt(0)
	v_mfma_f32_16x16x32_bf16 v[114:117], v[214:217], v[180:183], v[114:117]
	v_mfma_f32_16x16x32_bf16 v[106:109], v[222:225], v[180:183], v[106:109]
	v_mfma_f32_16x16x32_bf16 v[98:101], v[214:217], v[190:193], v[98:101]
	v_mfma_f32_16x16x32_bf16 v[90:93], v[222:225], v[190:193], v[90:93]
	v_mfma_f32_16x16x32_bf16 v[82:85], v[214:217], v[198:201], v[82:85]
	v_mfma_f32_16x16x32_bf16 v[74:77], v[222:225], v[198:201], v[74:77]
	v_mfma_f32_16x16x32_bf16 v[70:73], v[214:217], v[206:209], v[70:73]
	v_mfma_f32_16x16x32_bf16 v[66:69], v[222:225], v[206:209], v[66:69]
	v_mfma_f32_16x16x32_bf16 v[114:117], v[218:221], v[184:187], v[114:117]
	v_mfma_f32_16x16x32_bf16 v[106:109], v[226:229], v[184:187], v[106:109]
	v_mfma_f32_16x16x32_bf16 v[98:101], v[218:221], v[194:197], v[98:101]
	v_mfma_f32_16x16x32_bf16 v[90:93], v[226:229], v[194:197], v[90:93]
	v_mfma_f32_16x16x32_bf16 v[82:85], v[218:221], v[202:205], v[82:85]
	v_mfma_f32_16x16x32_bf16 v[74:77], v[226:229], v[202:205], v[74:77]
	v_mfma_f32_16x16x32_bf16 v[70:73], v[218:221], v[210:213], v[70:73]
	v_mfma_f32_16x16x32_bf16 v[66:69], v[226:229], v[210:213], v[66:69]
	s_barrier
	s_mov_b32 m0, s56
	ds_read_b128 v[180:183], v175 offset:49152
	ds_read_b128 v[184:187], v175 offset:50176
	ds_read_b128 v[190:193], v175 offset:51200
	ds_read_b128 v[194:197], v175 offset:52224
	ds_read_b128 v[198:201], v175 offset:53248
	ds_read_b128 v[202:205], v175 offset:54272
	ds_read_b128 v[206:209], v175 offset:55296
	ds_read_b128 v[210:213], v175 offset:56320
	global_load_lds_dwordx4 v146, s[100:101]
	s_mov_b32 m0, s57
	s_nop 0
	global_load_lds_dwordx4 v150, s[100:101]
	s_barrier
	s_waitcnt lgkmcnt(0)
	v_mfma_f32_16x16x32_bf16 v[62:65], v[130:133], v[180:183], v[62:65]
	v_mfma_f32_16x16x32_bf16 v[58:61], v[138:141], v[180:183], v[58:61]
	v_mfma_f32_16x16x32_bf16 v[54:57], v[130:133], v[190:193], v[54:57]
	v_mfma_f32_16x16x32_bf16 v[46:49], v[138:141], v[190:193], v[46:49]
	v_mfma_f32_16x16x32_bf16 v[38:41], v[130:133], v[198:201], v[38:41]
	v_mfma_f32_16x16x32_bf16 v[30:33], v[138:141], v[198:201], v[30:33]
	v_mfma_f32_16x16x32_bf16 v[22:25], v[130:133], v[206:209], v[22:25]
	v_mfma_f32_16x16x32_bf16 v[14:17], v[138:141], v[206:209], v[14:17]
	v_mfma_f32_16x16x32_bf16 v[62:65], v[134:137], v[184:187], v[62:65]
	v_mfma_f32_16x16x32_bf16 v[58:61], v[142:145], v[184:187], v[58:61]
	v_mfma_f32_16x16x32_bf16 v[54:57], v[134:137], v[194:197], v[54:57]
	v_mfma_f32_16x16x32_bf16 v[46:49], v[142:145], v[194:197], v[46:49]
	v_mfma_f32_16x16x32_bf16 v[38:41], v[134:137], v[202:205], v[38:41]
	v_mfma_f32_16x16x32_bf16 v[30:33], v[142:145], v[202:205], v[30:33]
	v_mfma_f32_16x16x32_bf16 v[22:25], v[134:137], v[210:213], v[22:25]
	v_mfma_f32_16x16x32_bf16 v[14:17], v[142:145], v[210:213], v[14:17]
	s_barrier
	s_add_u32 s6, s6, 0x40080
	s_addc_u32 s7, s7, 0
	s_add_i32 s8, s8, s49
	s_mov_b32 m0, s8
	s_nop 0
	global_load_lds_dwordx4 v148, s[6:7]
	s_add_i32 m0, s8, 0x2000
	s_nop 0
	global_load_lds_dwordx4 v152, s[6:7]
	s_add_i32 s73, s73, 2
	s_add_u32 s2, s2, 0x100
	s_addc_u32 s3, s3, 0
	s_add_u32 s71, s71, 0x100
	s_addc_u32 s72, s72, 0
	s_cmp_gt_u32 s73, 13
	s_waitcnt vmcnt(6)
	s_barrier
	v_mfma_f32_16x16x32_bf16 v[50:53], v[214:217], v[180:183], v[50:53]
	v_mfma_f32_16x16x32_bf16 v[42:45], v[222:225], v[180:183], v[42:45]
	v_mfma_f32_16x16x32_bf16 v[34:37], v[214:217], v[190:193], v[34:37]
	v_mfma_f32_16x16x32_bf16 v[26:29], v[222:225], v[190:193], v[26:29]
	v_mfma_f32_16x16x32_bf16 v[18:21], v[214:217], v[198:201], v[18:21]
	v_mfma_f32_16x16x32_bf16 v[10:13], v[222:225], v[198:201], v[10:13]
	v_mfma_f32_16x16x32_bf16 v[6:9], v[214:217], v[206:209], v[6:9]
	v_mfma_f32_16x16x32_bf16 v[2:5], v[222:225], v[206:209], v[2:5]
	v_mfma_f32_16x16x32_bf16 v[50:53], v[218:221], v[184:187], v[50:53]
	v_mfma_f32_16x16x32_bf16 v[42:45], v[226:229], v[184:187], v[42:45]
	v_mfma_f32_16x16x32_bf16 v[34:37], v[218:221], v[194:197], v[34:37]
	v_mfma_f32_16x16x32_bf16 v[26:29], v[226:229], v[194:197], v[26:29]
	v_mfma_f32_16x16x32_bf16 v[18:21], v[218:221], v[202:205], v[18:21]
	v_mfma_f32_16x16x32_bf16 v[10:13], v[226:229], v[202:205], v[10:13]
	v_mfma_f32_16x16x32_bf16 v[6:9], v[218:221], v[210:213], v[6:9]
	v_mfma_f32_16x16x32_bf16 v[2:5], v[226:229], v[210:213], v[2:5]
	s_barrier
	s_cbranch_scc0 .LBB0_212

.Lpeel_p8:
	ds_read_b128 v[130:133], v181
	ds_read_b128 v[134:137], v181 offset:1024
	ds_read_b128 v[138:141], v181 offset:2048
	ds_read_b128 v[142:145], v181 offset:3072
	s_add_u32 s2, s0, 0xfffc0080
	s_addc_u32 s3, s1, -1
	s_cmp_eq_u32 s74, 12
	s_cselect_b32 s45, s33, s3
	s_cselect_b32 s44, s39, s2
	s_cselect_b32 s3, s37, s73
	s_cselect_b32 s2, s71, s72
	s_add_i32 m0, s52, 0xc000
	ds_read_b128 v[146:149], v183
	ds_read_b128 v[150:153], v183 offset:1024
	ds_read_b128 v[154:157], v183 offset:2048
	ds_read_b128 v[158:161], v183 offset:3072
	ds_read_b128 v[162:165], v183 offset:4096
	ds_read_b128 v[166:169], v183 offset:5120
	ds_read_b128 v[170:173], v183 offset:6144
	ds_read_b128 v[174:177], v183 offset:7168
	global_load_lds_dwordx4 v192, s[0:1]
	s_add_i32 m0, s52, 0xe000
	s_nop 0
	global_load_lds_dwordx4 v194, s[0:1]
	s_waitcnt lgkmcnt(8)
	s_barrier
	s_waitcnt lgkmcnt(0)
	v_mfma_f32_16x16x32_bf16 v[62:65], v[130:133], v[146:149], 0
	v_mfma_f32_16x16x32_bf16 v[30:33], v[138:141], v[146:149], 0
	v_mfma_f32_16x16x32_bf16 v[54:57], v[130:133], v[154:157], 0
	v_mfma_f32_16x16x32_bf16 v[22:25], v[138:141], v[154:157], 0
	v_mfma_f32_16x16x32_bf16 v[46:49], v[130:133], v[162:165], 0
	v_mfma_f32_16x16x32_bf16 v[14:17], v[138:141], v[162:165], 0
	v_mfma_f32_16x16x32_bf16 v[38:41], v[130:133], v[170:173], 0
	v_mfma_f32_16x16x32_bf16 v[6:9], v[138:141], v[170:173], 0
	v_mfma_f32_16x16x32_bf16 v[62:65], v[134:137], v[150:153], v[62:65]
	v_mfma_f32_16x16x32_bf16 v[30:33], v[142:145], v[150:153], v[30:33]
	v_mfma_f32_16x16x32_bf16 v[54:57], v[134:137], v[158:161], v[54:57]
	v_mfma_f32_16x16x32_bf16 v[22:25], v[142:145], v[158:161], v[22:25]
	v_mfma_f32_16x16x32_bf16 v[46:49], v[134:137], v[166:169], v[46:49]
	v_mfma_f32_16x16x32_bf16 v[14:17], v[142:145], v[166:169], v[14:17]
	v_mfma_f32_16x16x32_bf16 v[38:41], v[134:137], v[174:177], v[38:41]
	v_mfma_f32_16x16x32_bf16 v[6:9], v[142:145], v[174:177], v[6:9]
	s_barrier
	s_add_i32 s75, s66, s51
	s_add_u32 s98, s2, 0x80
	s_addc_u32 s99, s3, 0
	s_mov_b32 m0, s75
	ds_read_b128 v[200:203], v206
	ds_read_b128 v[212:215], v206 offset:1024
	ds_read_b128 v[216:219], v206 offset:2048
	ds_read_b128 v[220:223], v206 offset:3072
	global_load_lds_dwordx4 v186, s[2:3]
	s_add_i32 m0, s75, 0x2000
	s_nop 0
	global_load_lds_dwordx4 v190, s[2:3]
	s_barrier
	s_waitcnt lgkmcnt(0)
	v_mfma_f32_16x16x32_bf16 v[58:61], v[200:203], v[146:149], 0
	v_mfma_f32_16x16x32_bf16 v[26:29], v[216:219], v[146:149], 0
	v_mfma_f32_16x16x32_bf16 v[50:53], v[200:203], v[154:157], 0
	v_mfma_f32_16x16x32_bf16 v[18:21], v[216:219], v[154:157], 0
	v_mfma_f32_16x16x32_bf16 v[42:45], v[200:203], v[162:165], 0
	v_mfma_f32_16x16x32_bf16 v[10:13], v[216:219], v[162:165], 0
	v_mfma_f32_16x16x32_bf16 v[34:37], v[200:203], v[170:173], 0
	v_mfma_f32_16x16x32_bf16 v[2:5], v[216:219], v[170:173], 0
	v_mfma_f32_16x16x32_bf16 v[58:61], v[212:215], v[150:153], v[58:61]
	v_mfma_f32_16x16x32_bf16 v[26:29], v[220:223], v[150:153], v[26:29]
	v_mfma_f32_16x16x32_bf16 v[50:53], v[212:215], v[158:161], v[50:53]
	v_mfma_f32_16x16x32_bf16 v[18:21], v[220:223], v[158:161], v[18:21]
	v_mfma_f32_16x16x32_bf16 v[42:45], v[212:215], v[166:169], v[42:45]
	v_mfma_f32_16x16x32_bf16 v[10:13], v[220:223], v[166:169], v[10:13]
	v_mfma_f32_16x16x32_bf16 v[34:37], v[212:215], v[174:177], v[34:37]
	v_mfma_f32_16x16x32_bf16 v[2:5], v[220:223], v[174:177], v[2:5]
	s_barrier
	s_mov_b32 m0, s52
	s_add_u32 s100, s44, 0x80
	s_addc_u32 s101, s45, 0
	ds_read_b128 v[146:149], v183 offset:16384
	ds_read_b128 v[150:153], v183 offset:17408
	ds_read_b128 v[154:157], v183 offset:18432
	ds_read_b128 v[158:161], v183 offset:19456
	ds_read_b128 v[162:165], v183 offset:20480
	ds_read_b128 v[166:169], v183 offset:21504
	ds_read_b128 v[170:173], v183 offset:22528
	ds_read_b128 v[174:177], v183 offset:23552
	global_load_lds_dwordx4 v184, s[44:45]
	s_mov_b32 m0, s53
	s_nop 0
	global_load_lds_dwordx4 v188, s[44:45]
	s_barrier
	s_waitcnt lgkmcnt(0)
	v_mfma_f32_16x16x32_bf16 v[126:129], v[130:133], v[146:149], 0
	v_mfma_f32_16x16x32_bf16 v[102:105], v[138:141], v[146:149], 0
	v_mfma_f32_16x16x32_bf16 v[122:125], v[130:133], v[154:157], 0
	v_mfma_f32_16x16x32_bf16 v[90:93], v[138:141], v[154:157], 0
	v_mfma_f32_16x16x32_bf16 v[118:121], v[130:133], v[162:165], 0
	v_mfma_f32_16x16x32_bf16 v[78:81], v[138:141], v[162:165], 0
	v_mfma_f32_16x16x32_bf16 v[106:109], v[130:133], v[170:173], 0
	v_mfma_f32_16x16x32_bf16 v[70:73], v[138:141], v[170:173], 0
	v_mfma_f32_16x16x32_bf16 v[126:129], v[134:137], v[150:153], v[126:129]
	v_mfma_f32_16x16x32_bf16 v[102:105], v[142:145], v[150:153], v[102:105]
	v_mfma_f32_16x16x32_bf16 v[122:125], v[134:137], v[158:161], v[122:125]
	v_mfma_f32_16x16x32_bf16 v[90:93], v[142:145], v[158:161], v[90:93]
	v_mfma_f32_16x16x32_bf16 v[118:121], v[134:137], v[166:169], v[118:121]
	v_mfma_f32_16x16x32_bf16 v[78:81], v[142:145], v[166:169], v[78:81]
	v_mfma_f32_16x16x32_bf16 v[106:109], v[134:137], v[174:177], v[106:109]
	v_mfma_f32_16x16x32_bf16 v[70:73], v[142:145], v[174:177], v[70:73]
	s_barrier
	s_add_u32 s76, s2, 0x40000
	s_addc_u32 s77, s3, 0
	s_add_i32 s75, s67, s51
	s_mov_b32 m0, s75
	s_nop 0
	global_load_lds_dwordx4 v186, s[76:77]
	s_add_i32 m0, s75, 0x2000
	s_nop 0
	global_load_lds_dwordx4 v190, s[76:77]
	s_waitcnt vmcnt(6)
	s_barrier
	v_mfma_f32_16x16x32_bf16 v[114:117], v[200:203], v[146:149], 0
	v_mfma_f32_16x16x32_bf16 v[86:89], v[216:219], v[146:149], 0
	v_mfma_f32_16x16x32_bf16 v[110:113], v[200:203], v[154:157], 0
	v_mfma_f32_16x16x32_bf16 v[82:85], v[216:219], v[154:157], 0
	v_mfma_f32_16x16x32_bf16 v[98:101], v[200:203], v[162:165], 0
	v_mfma_f32_16x16x32_bf16 v[74:77], v[216:219], v[162:165], 0
	v_mfma_f32_16x16x32_bf16 v[94:97], v[200:203], v[170:173], 0
	v_mfma_f32_16x16x32_bf16 v[66:69], v[216:219], v[170:173], 0
	v_mfma_f32_16x16x32_bf16 v[114:117], v[212:215], v[150:153], v[114:117]
	v_mfma_f32_16x16x32_bf16 v[86:89], v[220:223], v[150:153], v[86:89]
	v_mfma_f32_16x16x32_bf16 v[110:113], v[212:215], v[158:161], v[110:113]
	v_mfma_f32_16x16x32_bf16 v[82:85], v[220:223], v[158:161], v[82:85]
	v_mfma_f32_16x16x32_bf16 v[98:101], v[212:215], v[166:169], v[98:101]
	v_mfma_f32_16x16x32_bf16 v[74:77], v[220:223], v[166:169], v[74:77]
	v_mfma_f32_16x16x32_bf16 v[94:97], v[212:215], v[174:177], v[94:97]
	v_mfma_f32_16x16x32_bf16 v[66:69], v[220:223], v[174:177], v[66:69]
	s_barrier
	s_add_i32 s75, 0, 0x18000
	v_add_u32_e32 v142, s75, v1
	ds_read_b128 v[130:133], v142
	ds_read_b128 v[134:137], v142 offset:1024
	ds_read_b128 v[138:141], v142 offset:2048
	ds_read_b128 v[142:145], v142 offset:3072
	s_add_u32 s44, s44, 0x40000
	s_addc_u32 s45, s45, 0
	s_mov_b32 m0, s54
	ds_read_b128 v[146:149], v183 offset:32768
	ds_read_b128 v[150:153], v183 offset:33792
	ds_read_b128 v[154:157], v183 offset:34816
	ds_read_b128 v[158:161], v183 offset:35840
	ds_read_b128 v[162:165], v183 offset:36864
	ds_read_b128 v[166:169], v183 offset:37888
	ds_read_b128 v[170:173], v183 offset:38912
	ds_read_b128 v[174:177], v183 offset:39936
	global_load_lds_dwordx4 v184, s[44:45]
	s_mov_b32 m0, s55
	s_nop 0
	global_load_lds_dwordx4 v188, s[44:45]
	s_waitcnt lgkmcnt(8)
	s_barrier
	s_waitcnt lgkmcnt(0)
	v_mfma_f32_16x16x32_bf16 v[62:65], v[130:133], v[146:149], v[62:65]
	v_mfma_f32_16x16x32_bf16 v[30:33], v[138:141], v[146:149], v[30:33]
	v_mfma_f32_16x16x32_bf16 v[54:57], v[130:133], v[154:157], v[54:57]
	v_mfma_f32_16x16x32_bf16 v[22:25], v[138:141], v[154:157], v[22:25]
	v_mfma_f32_16x16x32_bf16 v[46:49], v[130:133], v[162:165], v[46:49]
	v_mfma_f32_16x16x32_bf16 v[14:17], v[138:141], v[162:165], v[14:17]
	v_mfma_f32_16x16x32_bf16 v[38:41], v[130:133], v[170:173], v[38:41]
	v_mfma_f32_16x16x32_bf16 v[6:9], v[138:141], v[170:173], v[6:9]
	v_mfma_f32_16x16x32_bf16 v[62:65], v[134:137], v[150:153], v[62:65]
	v_mfma_f32_16x16x32_bf16 v[30:33], v[142:145], v[150:153], v[30:33]
	v_mfma_f32_16x16x32_bf16 v[54:57], v[134:137], v[158:161], v[54:57]
	v_mfma_f32_16x16x32_bf16 v[22:25], v[142:145], v[158:161], v[22:25]
	v_mfma_f32_16x16x32_bf16 v[46:49], v[134:137], v[166:169], v[46:49]
	v_mfma_f32_16x16x32_bf16 v[14:17], v[142:145], v[166:169], v[14:17]
	v_mfma_f32_16x16x32_bf16 v[38:41], v[134:137], v[174:177], v[38:41]
	v_mfma_f32_16x16x32_bf16 v[6:9], v[142:145], v[174:177], v[6:9]
	s_barrier
	s_add_i32 s44, 0, 0x1c000
	s_add_i32 s45, s75, s51
	v_add_u32_e32 v207, s44, v1
	s_mov_b32 m0, s45
	ds_read_b128 v[200:203], v207
	ds_read_b128 v[212:215], v207 offset:1024
	ds_read_b128 v[216:219], v207 offset:2048
	ds_read_b128 v[220:223], v207 offset:3072
	global_load_lds_dwordx4 v186, s[98:99]
	s_add_i32 m0, s45, 0x2000
	s_nop 0
	global_load_lds_dwordx4 v190, s[98:99]
	s_barrier
	s_waitcnt lgkmcnt(0)
	v_mfma_f32_16x16x32_bf16 v[58:61], v[200:203], v[146:149], v[58:61]
	v_mfma_f32_16x16x32_bf16 v[26:29], v[216:219], v[146:149], v[26:29]
	v_mfma_f32_16x16x32_bf16 v[50:53], v[200:203], v[154:157], v[50:53]
	v_mfma_f32_16x16x32_bf16 v[18:21], v[216:219], v[154:157], v[18:21]
	v_mfma_f32_16x16x32_bf16 v[42:45], v[200:203], v[162:165], v[42:45]
	v_mfma_f32_16x16x32_bf16 v[10:13], v[216:219], v[162:165], v[10:13]
	v_mfma_f32_16x16x32_bf16 v[34:37], v[200:203], v[170:173], v[34:37]
	v_mfma_f32_16x16x32_bf16 v[2:5], v[216:219], v[170:173], v[2:5]
	v_mfma_f32_16x16x32_bf16 v[58:61], v[212:215], v[150:153], v[58:61]
	v_mfma_f32_16x16x32_bf16 v[26:29], v[220:223], v[150:153], v[26:29]
	v_mfma_f32_16x16x32_bf16 v[50:53], v[212:215], v[158:161], v[50:53]
	v_mfma_f32_16x16x32_bf16 v[18:21], v[220:223], v[158:161], v[18:21]
	v_mfma_f32_16x16x32_bf16 v[42:45], v[212:215], v[166:169], v[42:45]
	v_mfma_f32_16x16x32_bf16 v[10:13], v[220:223], v[166:169], v[10:13]
	v_mfma_f32_16x16x32_bf16 v[34:37], v[212:215], v[174:177], v[34:37]
	v_mfma_f32_16x16x32_bf16 v[2:5], v[220:223], v[174:177], v[2:5]
	s_barrier
	s_mov_b32 m0, s59
	ds_read_b128 v[146:149], v183 offset:49152
	ds_read_b128 v[150:153], v183 offset:50176
	ds_read_b128 v[154:157], v183 offset:51200
	ds_read_b128 v[158:161], v183 offset:52224
	ds_read_b128 v[162:165], v183 offset:53248
	ds_read_b128 v[166:169], v183 offset:54272
	ds_read_b128 v[170:173], v183 offset:55296
	ds_read_b128 v[174:177], v183 offset:56320
	global_load_lds_dwordx4 v184, s[100:101]
	s_mov_b32 m0, s60
	s_nop 0
	global_load_lds_dwordx4 v188, s[100:101]
	s_barrier
	s_waitcnt lgkmcnt(0)
	v_mfma_f32_16x16x32_bf16 v[126:129], v[130:133], v[146:149], v[126:129]
	v_mfma_f32_16x16x32_bf16 v[102:105], v[138:141], v[146:149], v[102:105]
	v_mfma_f32_16x16x32_bf16 v[122:125], v[130:133], v[154:157], v[122:125]
	v_mfma_f32_16x16x32_bf16 v[90:93], v[138:141], v[154:157], v[90:93]
	v_mfma_f32_16x16x32_bf16 v[118:121], v[130:133], v[162:165], v[118:121]
	v_mfma_f32_16x16x32_bf16 v[78:81], v[138:141], v[162:165], v[78:81]
	v_mfma_f32_16x16x32_bf16 v[106:109], v[130:133], v[170:173], v[106:109]
	v_mfma_f32_16x16x32_bf16 v[70:73], v[138:141], v[170:173], v[70:73]
	v_mfma_f32_16x16x32_bf16 v[126:129], v[134:137], v[150:153], v[126:129]
	v_mfma_f32_16x16x32_bf16 v[102:105], v[142:145], v[150:153], v[102:105]
	v_mfma_f32_16x16x32_bf16 v[122:125], v[134:137], v[158:161], v[122:125]
	v_mfma_f32_16x16x32_bf16 v[90:93], v[142:145], v[158:161], v[90:93]
	v_mfma_f32_16x16x32_bf16 v[118:121], v[134:137], v[166:169], v[118:121]
	v_mfma_f32_16x16x32_bf16 v[78:81], v[142:145], v[166:169], v[78:81]
	v_mfma_f32_16x16x32_bf16 v[106:109], v[134:137], v[174:177], v[106:109]
	v_mfma_f32_16x16x32_bf16 v[70:73], v[142:145], v[174:177], v[70:73]
	s_barrier
	s_add_u32 s2, s2, 0x40080
	s_addc_u32 s3, s3, 0
	s_add_i32 s44, s44, s51
	s_mov_b32 m0, s44
	s_nop 0
	global_load_lds_dwordx4 v186, s[2:3]
	s_add_i32 m0, s44, 0x2000
	s_nop 0
	global_load_lds_dwordx4 v190, s[2:3]
	s_add_i32 s74, s74, 2
	s_add_u32 s0, s0, 0x100
	s_addc_u32 s1, s1, 0
	s_add_u32 s72, s72, 0x100
	s_addc_u32 s73, s73, 0
	s_cmp_gt_u32 s74, 13
	s_waitcnt vmcnt(6)
	s_barrier
	v_mfma_f32_16x16x32_bf16 v[114:117], v[200:203], v[146:149], v[114:117]
	v_mfma_f32_16x16x32_bf16 v[86:89], v[216:219], v[146:149], v[86:89]
	v_mfma_f32_16x16x32_bf16 v[110:113], v[200:203], v[154:157], v[110:113]
	v_mfma_f32_16x16x32_bf16 v[82:85], v[216:219], v[154:157], v[82:85]
	v_mfma_f32_16x16x32_bf16 v[98:101], v[200:203], v[162:165], v[98:101]
	v_mfma_f32_16x16x32_bf16 v[74:77], v[216:219], v[162:165], v[74:77]
	v_mfma_f32_16x16x32_bf16 v[94:97], v[200:203], v[170:173], v[94:97]
	v_mfma_f32_16x16x32_bf16 v[66:69], v[216:219], v[170:173], v[66:69]
	v_mfma_f32_16x16x32_bf16 v[114:117], v[212:215], v[150:153], v[114:117]
	v_mfma_f32_16x16x32_bf16 v[86:89], v[220:223], v[150:153], v[86:89]
	v_mfma_f32_16x16x32_bf16 v[110:113], v[212:215], v[158:161], v[110:113]
	v_mfma_f32_16x16x32_bf16 v[82:85], v[220:223], v[158:161], v[82:85]
	v_mfma_f32_16x16x32_bf16 v[98:101], v[212:215], v[166:169], v[98:101]
	v_mfma_f32_16x16x32_bf16 v[74:77], v[220:223], v[166:169], v[74:77]
	v_mfma_f32_16x16x32_bf16 v[94:97], v[212:215], v[174:177], v[94:97]
	v_mfma_f32_16x16x32_bf16 v[66:69], v[220:223], v[174:177], v[66:69]
	s_barrier
	s_cbranch_scc1 .Lpeel_p8_exit
.LBB0_1090:
	ds_read_b128 v[130:133], v181
	ds_read_b128 v[134:137], v181 offset:1024
	ds_read_b128 v[138:141], v181 offset:2048
	ds_read_b128 v[142:145], v181 offset:3072
	s_add_u32 s2, s0, 0xfffc0080
	s_addc_u32 s3, s1, -1
	s_cmp_eq_u32 s74, 12
	s_cselect_b32 s45, s33, s3
	s_cselect_b32 s44, s39, s2
	s_cselect_b32 s3, s37, s73
	s_cselect_b32 s2, s71, s72
	s_add_i32 m0, s52, 0xc000
	ds_read_b128 v[146:149], v183
	ds_read_b128 v[150:153], v183 offset:1024
	ds_read_b128 v[154:157], v183 offset:2048
	ds_read_b128 v[158:161], v183 offset:3072
	ds_read_b128 v[162:165], v183 offset:4096
	ds_read_b128 v[166:169], v183 offset:5120
	ds_read_b128 v[170:173], v183 offset:6144
	ds_read_b128 v[174:177], v183 offset:7168
	global_load_lds_dwordx4 v192, s[0:1]
	s_add_i32 m0, s52, 0xe000
	s_nop 0
	global_load_lds_dwordx4 v194, s[0:1]
	s_waitcnt lgkmcnt(8)
	s_barrier
	s_waitcnt lgkmcnt(0)
	v_mfma_f32_16x16x32_bf16 v[62:65], v[130:133], v[146:149], v[62:65]
	v_mfma_f32_16x16x32_bf16 v[30:33], v[138:141], v[146:149], v[30:33]
	v_mfma_f32_16x16x32_bf16 v[54:57], v[130:133], v[154:157], v[54:57]
	v_mfma_f32_16x16x32_bf16 v[22:25], v[138:141], v[154:157], v[22:25]
	v_mfma_f32_16x16x32_bf16 v[46:49], v[130:133], v[162:165], v[46:49]
	v_mfma_f32_16x16x32_bf16 v[14:17], v[138:141], v[162:165], v[14:17]
	v_mfma_f32_16x16x32_bf16 v[38:41], v[130:133], v[170:173], v[38:41]
	v_mfma_f32_16x16x32_bf16 v[6:9], v[138:141], v[170:173], v[6:9]
	v_mfma_f32_16x16x32_bf16 v[62:65], v[134:137], v[150:153], v[62:65]
	v_mfma_f32_16x16x32_bf16 v[30:33], v[142:145], v[150:153], v[30:33]
	v_mfma_f32_16x16x32_bf16 v[54:57], v[134:137], v[158:161], v[54:57]
	v_mfma_f32_16x16x32_bf16 v[22:25], v[142:145], v[158:161], v[22:25]
	v_mfma_f32_16x16x32_bf16 v[46:49], v[134:137], v[166:169], v[46:49]
	v_mfma_f32_16x16x32_bf16 v[14:17], v[142:145], v[166:169], v[14:17]
	v_mfma_f32_16x16x32_bf16 v[38:41], v[134:137], v[174:177], v[38:41]
	v_mfma_f32_16x16x32_bf16 v[6:9], v[142:145], v[174:177], v[6:9]
	s_barrier
	s_add_i32 s75, s66, s51
	s_add_u32 s98, s2, 0x80
	s_addc_u32 s99, s3, 0
	s_mov_b32 m0, s75
	ds_read_b128 v[200:203], v206
	ds_read_b128 v[212:215], v206 offset:1024
	ds_read_b128 v[216:219], v206 offset:2048
	ds_read_b128 v[220:223], v206 offset:3072
	global_load_lds_dwordx4 v186, s[2:3]
	s_add_i32 m0, s75, 0x2000
	s_nop 0
	global_load_lds_dwordx4 v190, s[2:3]
	s_barrier
	s_waitcnt lgkmcnt(0)
	v_mfma_f32_16x16x32_bf16 v[58:61], v[200:203], v[146:149], v[58:61]
	v_mfma_f32_16x16x32_bf16 v[26:29], v[216:219], v[146:149], v[26:29]
	v_mfma_f32_16x16x32_bf16 v[50:53], v[200:203], v[154:157], v[50:53]
	v_mfma_f32_16x16x32_bf16 v[18:21], v[216:219], v[154:157], v[18:21]
	v_mfma_f32_16x16x32_bf16 v[42:45], v[200:203], v[162:165], v[42:45]
	v_mfma_f32_16x16x32_bf16 v[10:13], v[216:219], v[162:165], v[10:13]
	v_mfma_f32_16x16x32_bf16 v[34:37], v[200:203], v[170:173], v[34:37]
	v_mfma_f32_16x16x32_bf16 v[2:5], v[216:219], v[170:173], v[2:5]
	v_mfma_f32_16x16x32_bf16 v[58:61], v[212:215], v[150:153], v[58:61]
	v_mfma_f32_16x16x32_bf16 v[26:29], v[220:223], v[150:153], v[26:29]
	v_mfma_f32_16x16x32_bf16 v[50:53], v[212:215], v[158:161], v[50:53]
	v_mfma_f32_16x16x32_bf16 v[18:21], v[220:223], v[158:161], v[18:21]
	v_mfma_f32_16x16x32_bf16 v[42:45], v[212:215], v[166:169], v[42:45]
	v_mfma_f32_16x16x32_bf16 v[10:13], v[220:223], v[166:169], v[10:13]
	v_mfma_f32_16x16x32_bf16 v[34:37], v[212:215], v[174:177], v[34:37]
	v_mfma_f32_16x16x32_bf16 v[2:5], v[220:223], v[174:177], v[2:5]
	s_barrier
	s_mov_b32 m0, s52
	s_add_u32 s100, s44, 0x80
	s_addc_u32 s101, s45, 0
	ds_read_b128 v[146:149], v183 offset:16384
	ds_read_b128 v[150:153], v183 offset:17408
	ds_read_b128 v[154:157], v183 offset:18432
	ds_read_b128 v[158:161], v183 offset:19456
	ds_read_b128 v[162:165], v183 offset:20480
	ds_read_b128 v[166:169], v183 offset:21504
	ds_read_b128 v[170:173], v183 offset:22528
	ds_read_b128 v[174:177], v183 offset:23552
	global_load_lds_dwordx4 v184, s[44:45]
	s_mov_b32 m0, s53
	s_nop 0
	global_load_lds_dwordx4 v188, s[44:45]
	s_barrier
	s_waitcnt lgkmcnt(0)
	v_mfma_f32_16x16x32_bf16 v[126:129], v[130:133], v[146:149], v[126:129]
	v_mfma_f32_16x16x32_bf16 v[102:105], v[138:141], v[146:149], v[102:105]
	v_mfma_f32_16x16x32_bf16 v[122:125], v[130:133], v[154:157], v[122:125]
	v_mfma_f32_16x16x32_bf16 v[90:93], v[138:141], v[154:157], v[90:93]
	v_mfma_f32_16x16x32_bf16 v[118:121], v[130:133], v[162:165], v[118:121]
	v_mfma_f32_16x16x32_bf16 v[78:81], v[138:141], v[162:165], v[78:81]
	v_mfma_f32_16x16x32_bf16 v[106:109], v[130:133], v[170:173], v[106:109]
	v_mfma_f32_16x16x32_bf16 v[70:73], v[138:141], v[170:173], v[70:73]
	v_mfma_f32_16x16x32_bf16 v[126:129], v[134:137], v[150:153], v[126:129]
	v_mfma_f32_16x16x32_bf16 v[102:105], v[142:145], v[150:153], v[102:105]
	v_mfma_f32_16x16x32_bf16 v[122:125], v[134:137], v[158:161], v[122:125]
	v_mfma_f32_16x16x32_bf16 v[90:93], v[142:145], v[158:161], v[90:93]
	v_mfma_f32_16x16x32_bf16 v[118:121], v[134:137], v[166:169], v[118:121]
	v_mfma_f32_16x16x32_bf16 v[78:81], v[142:145], v[166:169], v[78:81]
	v_mfma_f32_16x16x32_bf16 v[106:109], v[134:137], v[174:177], v[106:109]
	v_mfma_f32_16x16x32_bf16 v[70:73], v[142:145], v[174:177], v[70:73]
	s_barrier
	s_add_u32 s76, s2, 0x40000
	s_addc_u32 s77, s3, 0
	s_add_i32 s75, s67, s51
	s_mov_b32 m0, s75
	s_nop 0
	global_load_lds_dwordx4 v186, s[76:77]
	s_add_i32 m0, s75, 0x2000
	s_nop 0
	global_load_lds_dwordx4 v190, s[76:77]
	s_waitcnt vmcnt(6)
	s_barrier
	v_mfma_f32_16x16x32_bf16 v[114:117], v[200:203], v[146:149], v[114:117]
	v_mfma_f32_16x16x32_bf16 v[86:89], v[216:219], v[146:149], v[86:89]
	v_mfma_f32_16x16x32_bf16 v[110:113], v[200:203], v[154:157], v[110:113]
	v_mfma_f32_16x16x32_bf16 v[82:85], v[216:219], v[154:157], v[82:85]
	v_mfma_f32_16x16x32_bf16 v[98:101], v[200:203], v[162:165], v[98:101]
	v_mfma_f32_16x16x32_bf16 v[74:77], v[216:219], v[162:165], v[74:77]
	v_mfma_f32_16x16x32_bf16 v[94:97], v[200:203], v[170:173], v[94:97]
	v_mfma_f32_16x16x32_bf16 v[66:69], v[216:219], v[170:173], v[66:69]
	v_mfma_f32_16x16x32_bf16 v[114:117], v[212:215], v[150:153], v[114:117]
	v_mfma_f32_16x16x32_bf16 v[86:89], v[220:223], v[150:153], v[86:89]
	v_mfma_f32_16x16x32_bf16 v[110:113], v[212:215], v[158:161], v[110:113]
	v_mfma_f32_16x16x32_bf16 v[82:85], v[220:223], v[158:161], v[82:85]
	v_mfma_f32_16x16x32_bf16 v[98:101], v[212:215], v[166:169], v[98:101]
	v_mfma_f32_16x16x32_bf16 v[74:77], v[220:223], v[166:169], v[74:77]
	v_mfma_f32_16x16x32_bf16 v[94:97], v[212:215], v[174:177], v[94:97]
	v_mfma_f32_16x16x32_bf16 v[66:69], v[220:223], v[174:177], v[66:69]
	s_barrier
	s_add_i32 s75, 0, 0x18000
	v_add_u32_e32 v142, s75, v1
	ds_read_b128 v[130:133], v142
	ds_read_b128 v[134:137], v142 offset:1024
	ds_read_b128 v[138:141], v142 offset:2048
	ds_read_b128 v[142:145], v142 offset:3072
	s_add_u32 s44, s44, 0x40000
	s_addc_u32 s45, s45, 0
	s_mov_b32 m0, s54
	ds_read_b128 v[146:149], v183 offset:32768
	ds_read_b128 v[150:153], v183 offset:33792
	ds_read_b128 v[154:157], v183 offset:34816
	ds_read_b128 v[158:161], v183 offset:35840
	ds_read_b128 v[162:165], v183 offset:36864
	ds_read_b128 v[166:169], v183 offset:37888
	ds_read_b128 v[170:173], v183 offset:38912
	ds_read_b128 v[174:177], v183 offset:39936
	global_load_lds_dwordx4 v184, s[44:45]
	s_mov_b32 m0, s55
	s_nop 0
	global_load_lds_dwordx4 v188, s[44:45]
	s_waitcnt lgkmcnt(8)
	s_barrier
	s_waitcnt lgkmcnt(0)
	v_mfma_f32_16x16x32_bf16 v[62:65], v[130:133], v[146:149], v[62:65]
	v_mfma_f32_16x16x32_bf16 v[30:33], v[138:141], v[146:149], v[30:33]
	v_mfma_f32_16x16x32_bf16 v[54:57], v[130:133], v[154:157], v[54:57]
	v_mfma_f32_16x16x32_bf16 v[22:25], v[138:141], v[154:157], v[22:25]
	v_mfma_f32_16x16x32_bf16 v[46:49], v[130:133], v[162:165], v[46:49]
	v_mfma_f32_16x16x32_bf16 v[14:17], v[138:141], v[162:165], v[14:17]
	v_mfma_f32_16x16x32_bf16 v[38:41], v[130:133], v[170:173], v[38:41]
	v_mfma_f32_16x16x32_bf16 v[6:9], v[138:141], v[170:173], v[6:9]
	v_mfma_f32_16x16x32_bf16 v[62:65], v[134:137], v[150:153], v[62:65]
	v_mfma_f32_16x16x32_bf16 v[30:33], v[142:145], v[150:153], v[30:33]
	v_mfma_f32_16x16x32_bf16 v[54:57], v[134:137], v[158:161], v[54:57]
	v_mfma_f32_16x16x32_bf16 v[22:25], v[142:145], v[158:161], v[22:25]
	v_mfma_f32_16x16x32_bf16 v[46:49], v[134:137], v[166:169], v[46:49]
	v_mfma_f32_16x16x32_bf16 v[14:17], v[142:145], v[166:169], v[14:17]
	v_mfma_f32_16x16x32_bf16 v[38:41], v[134:137], v[174:177], v[38:41]
	v_mfma_f32_16x16x32_bf16 v[6:9], v[142:145], v[174:177], v[6:9]
	s_barrier
	s_add_i32 s44, 0, 0x1c000
	s_add_i32 s45, s75, s51
	v_add_u32_e32 v207, s44, v1
	s_mov_b32 m0, s45
	ds_read_b128 v[200:203], v207
	ds_read_b128 v[212:215], v207 offset:1024
	ds_read_b128 v[216:219], v207 offset:2048
	ds_read_b128 v[220:223], v207 offset:3072
	global_load_lds_dwordx4 v186, s[98:99]
	s_add_i32 m0, s45, 0x2000
	s_nop 0
	global_load_lds_dwordx4 v190, s[98:99]
	s_barrier
	s_waitcnt lgkmcnt(0)
	v_mfma_f32_16x16x32_bf16 v[58:61], v[200:203], v[146:149], v[58:61]
	v_mfma_f32_16x16x32_bf16 v[26:29], v[216:219], v[146:149], v[26:29]
	v_mfma_f32_16x16x32_bf16 v[50:53], v[200:203], v[154:157], v[50:53]
	v_mfma_f32_16x16x32_bf16 v[18:21], v[216:219], v[154:157], v[18:21]
	v_mfma_f32_16x16x32_bf16 v[42:45], v[200:203], v[162:165], v[42:45]
	v_mfma_f32_16x16x32_bf16 v[10:13], v[216:219], v[162:165], v[10:13]
	v_mfma_f32_16x16x32_bf16 v[34:37], v[200:203], v[170:173], v[34:37]
	v_mfma_f32_16x16x32_bf16 v[2:5], v[216:219], v[170:173], v[2:5]
	v_mfma_f32_16x16x32_bf16 v[58:61], v[212:215], v[150:153], v[58:61]
	v_mfma_f32_16x16x32_bf16 v[26:29], v[220:223], v[150:153], v[26:29]
	v_mfma_f32_16x16x32_bf16 v[50:53], v[212:215], v[158:161], v[50:53]
	v_mfma_f32_16x16x32_bf16 v[18:21], v[220:223], v[158:161], v[18:21]
	v_mfma_f32_16x16x32_bf16 v[42:45], v[212:215], v[166:169], v[42:45]
	v_mfma_f32_16x16x32_bf16 v[10:13], v[220:223], v[166:169], v[10:13]
	v_mfma_f32_16x16x32_bf16 v[34:37], v[212:215], v[174:177], v[34:37]
	v_mfma_f32_16x16x32_bf16 v[2:5], v[220:223], v[174:177], v[2:5]
	s_barrier
	s_mov_b32 m0, s59
	ds_read_b128 v[146:149], v183 offset:49152
	ds_read_b128 v[150:153], v183 offset:50176
	ds_read_b128 v[154:157], v183 offset:51200
	ds_read_b128 v[158:161], v183 offset:52224
	ds_read_b128 v[162:165], v183 offset:53248
	ds_read_b128 v[166:169], v183 offset:54272
	ds_read_b128 v[170:173], v183 offset:55296
	ds_read_b128 v[174:177], v183 offset:56320
	global_load_lds_dwordx4 v184, s[100:101]
	s_mov_b32 m0, s60
	s_nop 0
	global_load_lds_dwordx4 v188, s[100:101]
	s_barrier
	s_waitcnt lgkmcnt(0)
	v_mfma_f32_16x16x32_bf16 v[126:129], v[130:133], v[146:149], v[126:129]
	v_mfma_f32_16x16x32_bf16 v[102:105], v[138:141], v[146:149], v[102:105]
	v_mfma_f32_16x16x32_bf16 v[122:125], v[130:133], v[154:157], v[122:125]
	v_mfma_f32_16x16x32_bf16 v[90:93], v[138:141], v[154:157], v[90:93]
	v_mfma_f32_16x16x32_bf16 v[118:121], v[130:133], v[162:165], v[118:121]
	v_mfma_f32_16x16x32_bf16 v[78:81], v[138:141], v[162:165], v[78:81]
	v_mfma_f32_16x16x32_bf16 v[106:109], v[130:133], v[170:173], v[106:109]
	v_mfma_f32_16x16x32_bf16 v[70:73], v[138:141], v[170:173], v[70:73]
	v_mfma_f32_16x16x32_bf16 v[126:129], v[134:137], v[150:153], v[126:129]
	v_mfma_f32_16x16x32_bf16 v[102:105], v[142:145], v[150:153], v[102:105]
	v_mfma_f32_16x16x32_bf16 v[122:125], v[134:137], v[158:161], v[122:125]
	v_mfma_f32_16x16x32_bf16 v[90:93], v[142:145], v[158:161], v[90:93]
	v_mfma_f32_16x16x32_bf16 v[118:121], v[134:137], v[166:169], v[118:121]
	v_mfma_f32_16x16x32_bf16 v[78:81], v[142:145], v[166:169], v[78:81]
	v_mfma_f32_16x16x32_bf16 v[106:109], v[134:137], v[174:177], v[106:109]
	v_mfma_f32_16x16x32_bf16 v[70:73], v[142:145], v[174:177], v[70:73]
	s_barrier
	s_add_u32 s2, s2, 0x40080
	s_addc_u32 s3, s3, 0
	s_add_i32 s44, s44, s51
	s_mov_b32 m0, s44
	s_nop 0
	global_load_lds_dwordx4 v186, s[2:3]
	s_add_i32 m0, s44, 0x2000
	s_nop 0
	global_load_lds_dwordx4 v190, s[2:3]
	s_add_i32 s74, s74, 2
	s_add_u32 s0, s0, 0x100
	s_addc_u32 s1, s1, 0
	s_add_u32 s72, s72, 0x100
	s_addc_u32 s73, s73, 0
	s_cmp_gt_u32 s74, 13
	s_waitcnt vmcnt(6)
	s_barrier
	v_mfma_f32_16x16x32_bf16 v[114:117], v[200:203], v[146:149], v[114:117]
	v_mfma_f32_16x16x32_bf16 v[86:89], v[216:219], v[146:149], v[86:89]
	v_mfma_f32_16x16x32_bf16 v[110:113], v[200:203], v[154:157], v[110:113]
	v_mfma_f32_16x16x32_bf16 v[82:85], v[216:219], v[154:157], v[82:85]
	v_mfma_f32_16x16x32_bf16 v[98:101], v[200:203], v[162:165], v[98:101]
	v_mfma_f32_16x16x32_bf16 v[74:77], v[216:219], v[162:165], v[74:77]
	v_mfma_f32_16x16x32_bf16 v[94:97], v[200:203], v[170:173], v[94:97]
	v_mfma_f32_16x16x32_bf16 v[66:69], v[216:219], v[170:173], v[66:69]
	v_mfma_f32_16x16x32_bf16 v[114:117], v[212:215], v[150:153], v[114:117]
	v_mfma_f32_16x16x32_bf16 v[86:89], v[220:223], v[150:153], v[86:89]
	v_mfma_f32_16x16x32_bf16 v[110:113], v[212:215], v[158:161], v[110:113]
	v_mfma_f32_16x16x32_bf16 v[82:85], v[220:223], v[158:161], v[82:85]
	v_mfma_f32_16x16x32_bf16 v[98:101], v[212:215], v[166:169], v[98:101]
	v_mfma_f32_16x16x32_bf16 v[74:77], v[220:223], v[166:169], v[74:77]
	v_mfma_f32_16x16x32_bf16 v[94:97], v[212:215], v[174:177], v[94:97]
	v_mfma_f32_16x16x32_bf16 v[66:69], v[220:223], v[174:177], v[66:69]
	s_barrier
	s_cbranch_scc0 .LBB0_1090

.Lpeel_p10:
	ds_read_b128 v[152:155], v149
	ds_read_b128 v[156:159], v149 offset:1024
	ds_read_b128 v[160:163], v149 offset:2048
	ds_read_b128 v[164:167], v149 offset:3072
	s_add_u32 s18, s16, 0xfff50080
	s_addc_u32 s19, s17, -1
	s_cmp_eq_u32 s54, 40
	s_cselect_b32 s21, s3, s19
	s_cselect_b32 s20, s2, s18
	s_cselect_b32 s19, s5, s53
	s_cselect_b32 s18, s4, s52
	s_add_i32 m0, s30, 0xc000
	ds_read_b128 v[168:171], v150
	ds_read_b128 v[172:175], v150 offset:1024
	ds_read_b128 v[180:183], v150 offset:2048
	ds_read_b128 v[184:187], v150 offset:3072
	ds_read_b128 v[188:191], v150 offset:4096
	ds_read_b128 v[192:195], v150 offset:5120
	ds_read_b128 v[196:199], v150 offset:6144
	ds_read_b128 v[200:203], v150 offset:7168
	global_load_lds_dwordx4 v138, s[16:17]
	s_add_i32 m0, s30, 0xe000
	s_nop 0
	global_load_lds_dwordx4 v140, s[16:17]
	s_waitcnt lgkmcnt(8)
	s_barrier
	s_waitcnt lgkmcnt(0)
	v_mfma_f32_16x16x32_bf16 v[126:129], v[152:155], v[168:171], 0
	v_mfma_f32_16x16x32_bf16 v[122:125], v[160:163], v[168:171], 0
	v_mfma_f32_16x16x32_bf16 v[114:117], v[152:155], v[180:183], 0
	v_mfma_f32_16x16x32_bf16 v[106:109], v[160:163], v[180:183], 0
	v_mfma_f32_16x16x32_bf16 v[98:101], v[152:155], v[188:191], 0
	v_mfma_f32_16x16x32_bf16 v[90:93], v[160:163], v[188:191], 0
	v_mfma_f32_16x16x32_bf16 v[82:85], v[152:155], v[196:199], 0
	v_mfma_f32_16x16x32_bf16 v[74:77], v[160:163], v[196:199], 0
	v_mfma_f32_16x16x32_bf16 v[126:129], v[156:159], v[172:175], v[126:129]
	v_mfma_f32_16x16x32_bf16 v[122:125], v[164:167], v[172:175], v[122:125]
	v_mfma_f32_16x16x32_bf16 v[114:117], v[156:159], v[184:187], v[114:117]
	v_mfma_f32_16x16x32_bf16 v[106:109], v[164:167], v[184:187], v[106:109]
	v_mfma_f32_16x16x32_bf16 v[98:101], v[156:159], v[192:195], v[98:101]
	v_mfma_f32_16x16x32_bf16 v[90:93], v[164:167], v[192:195], v[90:93]
	v_mfma_f32_16x16x32_bf16 v[82:85], v[156:159], v[200:203], v[82:85]
	v_mfma_f32_16x16x32_bf16 v[74:77], v[164:167], v[200:203], v[74:77]
	s_barrier
	s_add_i32 s55, s41, s27
	s_add_u32 s98, s18, 0x80
	s_addc_u32 s99, s19, 0
	s_mov_b32 m0, s55
	ds_read_b128 v[206:209], v151
	ds_read_b128 v[212:215], v151 offset:1024
	ds_read_b128 v[216:219], v151 offset:2048
	ds_read_b128 v[220:223], v151 offset:3072
	global_load_lds_dwordx4 v134, s[18:19]
	s_add_i32 m0, s55, 0x2000
	s_nop 0
	global_load_lds_dwordx4 v136, s[18:19]
	s_barrier
	s_waitcnt lgkmcnt(0)
	v_mfma_f32_16x16x32_bf16 v[118:121], v[206:209], v[168:171], 0
	v_mfma_f32_16x16x32_bf16 v[110:113], v[216:219], v[168:171], 0
	v_mfma_f32_16x16x32_bf16 v[102:105], v[206:209], v[180:183], 0
	v_mfma_f32_16x16x32_bf16 v[94:97], v[216:219], v[180:183], 0
	v_mfma_f32_16x16x32_bf16 v[86:89], v[206:209], v[188:191], 0
	v_mfma_f32_16x16x32_bf16 v[78:81], v[216:219], v[188:191], 0
	v_mfma_f32_16x16x32_bf16 v[70:73], v[206:209], v[196:199], 0
	v_mfma_f32_16x16x32_bf16 v[66:69], v[216:219], v[196:199], 0
	v_mfma_f32_16x16x32_bf16 v[118:121], v[212:215], v[172:175], v[118:121]
	v_mfma_f32_16x16x32_bf16 v[110:113], v[220:223], v[172:175], v[110:113]
	v_mfma_f32_16x16x32_bf16 v[102:105], v[212:215], v[184:187], v[102:105]
	v_mfma_f32_16x16x32_bf16 v[94:97], v[220:223], v[184:187], v[94:97]
	v_mfma_f32_16x16x32_bf16 v[86:89], v[212:215], v[192:195], v[86:89]
	v_mfma_f32_16x16x32_bf16 v[78:81], v[220:223], v[192:195], v[78:81]
	v_mfma_f32_16x16x32_bf16 v[70:73], v[212:215], v[200:203], v[70:73]
	v_mfma_f32_16x16x32_bf16 v[66:69], v[220:223], v[200:203], v[66:69]
	s_barrier
	s_mov_b32 m0, s30
	s_add_u32 s100, s20, 0x80
	s_addc_u32 s101, s21, 0
	ds_read_b128 v[168:171], v150 offset:16384
	ds_read_b128 v[172:175], v150 offset:17408
	ds_read_b128 v[180:183], v150 offset:18432
	ds_read_b128 v[184:187], v150 offset:19456
	ds_read_b128 v[188:191], v150 offset:20480
	ds_read_b128 v[192:195], v150 offset:21504
	ds_read_b128 v[196:199], v150 offset:22528
	ds_read_b128 v[200:203], v150 offset:23552
	global_load_lds_dwordx4 v130, s[20:21]
	s_mov_b32 m0, s31
	s_nop 0
	global_load_lds_dwordx4 v132, s[20:21]
	s_barrier
	s_waitcnt lgkmcnt(0)
	v_mfma_f32_16x16x32_bf16 v[62:65], v[152:155], v[168:171], 0
	v_mfma_f32_16x16x32_bf16 v[58:61], v[160:163], v[168:171], 0
	v_mfma_f32_16x16x32_bf16 v[50:53], v[152:155], v[180:183], 0
	v_mfma_f32_16x16x32_bf16 v[42:45], v[160:163], v[180:183], 0
	v_mfma_f32_16x16x32_bf16 v[34:37], v[152:155], v[188:191], 0
	v_mfma_f32_16x16x32_bf16 v[26:29], v[160:163], v[188:191], 0
	v_mfma_f32_16x16x32_bf16 v[18:21], v[152:155], v[196:199], 0
	v_mfma_f32_16x16x32_bf16 v[10:13], v[160:163], v[196:199], 0
	v_mfma_f32_16x16x32_bf16 v[62:65], v[156:159], v[172:175], v[62:65]
	v_mfma_f32_16x16x32_bf16 v[58:61], v[164:167], v[172:175], v[58:61]
	v_mfma_f32_16x16x32_bf16 v[50:53], v[156:159], v[184:187], v[50:53]
	v_mfma_f32_16x16x32_bf16 v[42:45], v[164:167], v[184:187], v[42:45]
	v_mfma_f32_16x16x32_bf16 v[34:37], v[156:159], v[192:195], v[34:37]
	v_mfma_f32_16x16x32_bf16 v[26:29], v[164:167], v[192:195], v[26:29]
	v_mfma_f32_16x16x32_bf16 v[18:21], v[156:159], v[200:203], v[18:21]
	v_mfma_f32_16x16x32_bf16 v[10:13], v[164:167], v[200:203], v[10:13]
	s_barrier
	s_add_u32 s56, s18, 0xb0000
	s_addc_u32 s57, s19, 0
	s_add_i32 s55, s42, s27
	s_mov_b32 m0, s55
	s_nop 0
	global_load_lds_dwordx4 v134, s[56:57]
	s_add_i32 m0, s55, 0x2000
	s_nop 0
	global_load_lds_dwordx4 v136, s[56:57]
	s_waitcnt vmcnt(6)
	s_barrier
	v_mfma_f32_16x16x32_bf16 v[54:57], v[206:209], v[168:171], 0
	v_mfma_f32_16x16x32_bf16 v[46:49], v[216:219], v[168:171], 0
	v_mfma_f32_16x16x32_bf16 v[38:41], v[206:209], v[180:183], 0
	v_mfma_f32_16x16x32_bf16 v[30:33], v[216:219], v[180:183], 0
	v_mfma_f32_16x16x32_bf16 v[22:25], v[206:209], v[188:191], 0
	v_mfma_f32_16x16x32_bf16 v[14:17], v[216:219], v[188:191], 0
	v_mfma_f32_16x16x32_bf16 v[6:9], v[206:209], v[196:199], 0
	v_mfma_f32_16x16x32_bf16 v[2:5], v[216:219], v[196:199], 0
	v_mfma_f32_16x16x32_bf16 v[54:57], v[212:215], v[172:175], v[54:57]
	v_mfma_f32_16x16x32_bf16 v[46:49], v[220:223], v[172:175], v[46:49]
	v_mfma_f32_16x16x32_bf16 v[38:41], v[212:215], v[184:187], v[38:41]
	v_mfma_f32_16x16x32_bf16 v[30:33], v[220:223], v[184:187], v[30:33]
	v_mfma_f32_16x16x32_bf16 v[22:25], v[212:215], v[192:195], v[22:25]
	v_mfma_f32_16x16x32_bf16 v[14:17], v[220:223], v[192:195], v[14:17]
	v_mfma_f32_16x16x32_bf16 v[6:9], v[212:215], v[200:203], v[6:9]
	v_mfma_f32_16x16x32_bf16 v[2:5], v[220:223], v[200:203], v[2:5]
	s_barrier
	s_add_i32 s55, 0, 0x18000
	v_add_u32_e32 v164, s55, v148
	ds_read_b128 v[152:155], v164
	ds_read_b128 v[156:159], v164 offset:1024
	ds_read_b128 v[160:163], v164 offset:2048
	ds_read_b128 v[164:167], v164 offset:3072
	s_add_u32 s20, s20, 0xb0000
	s_addc_u32 s21, s21, 0
	s_mov_b32 m0, s33
	ds_read_b128 v[168:171], v150 offset:32768
	ds_read_b128 v[172:175], v150 offset:33792
	ds_read_b128 v[180:183], v150 offset:34816
	ds_read_b128 v[184:187], v150 offset:35840
	ds_read_b128 v[188:191], v150 offset:36864
	ds_read_b128 v[192:195], v150 offset:37888
	ds_read_b128 v[196:199], v150 offset:38912
	ds_read_b128 v[200:203], v150 offset:39936
	global_load_lds_dwordx4 v130, s[20:21]
	s_mov_b32 m0, s34
	s_nop 0
	global_load_lds_dwordx4 v132, s[20:21]
	s_waitcnt lgkmcnt(8)
	s_barrier
	s_waitcnt lgkmcnt(0)
	v_mfma_f32_16x16x32_bf16 v[126:129], v[152:155], v[168:171], v[126:129]
	v_mfma_f32_16x16x32_bf16 v[122:125], v[160:163], v[168:171], v[122:125]
	v_mfma_f32_16x16x32_bf16 v[114:117], v[152:155], v[180:183], v[114:117]
	v_mfma_f32_16x16x32_bf16 v[106:109], v[160:163], v[180:183], v[106:109]
	v_mfma_f32_16x16x32_bf16 v[98:101], v[152:155], v[188:191], v[98:101]
	v_mfma_f32_16x16x32_bf16 v[90:93], v[160:163], v[188:191], v[90:93]
	v_mfma_f32_16x16x32_bf16 v[82:85], v[152:155], v[196:199], v[82:85]
	v_mfma_f32_16x16x32_bf16 v[74:77], v[160:163], v[196:199], v[74:77]
	v_mfma_f32_16x16x32_bf16 v[126:129], v[156:159], v[172:175], v[126:129]
	v_mfma_f32_16x16x32_bf16 v[122:125], v[164:167], v[172:175], v[122:125]
	v_mfma_f32_16x16x32_bf16 v[114:117], v[156:159], v[184:187], v[114:117]
	v_mfma_f32_16x16x32_bf16 v[106:109], v[164:167], v[184:187], v[106:109]
	v_mfma_f32_16x16x32_bf16 v[98:101], v[156:159], v[192:195], v[98:101]
	v_mfma_f32_16x16x32_bf16 v[90:93], v[164:167], v[192:195], v[90:93]
	v_mfma_f32_16x16x32_bf16 v[82:85], v[156:159], v[200:203], v[82:85]
	v_mfma_f32_16x16x32_bf16 v[74:77], v[164:167], v[200:203], v[74:77]
	s_barrier
	s_add_i32 s20, 0, 0x1c000
	s_add_i32 s21, s55, s27
	v_add_u32_e32 v179, s20, v148
	s_mov_b32 m0, s21
	ds_read_b128 v[206:209], v179
	ds_read_b128 v[212:215], v179 offset:1024
	ds_read_b128 v[216:219], v179 offset:2048
	ds_read_b128 v[220:223], v179 offset:3072
	global_load_lds_dwordx4 v134, s[98:99]
	s_add_i32 m0, s21, 0x2000
	s_nop 0
	global_load_lds_dwordx4 v136, s[98:99]
	s_barrier
	s_waitcnt lgkmcnt(0)
	v_mfma_f32_16x16x32_bf16 v[118:121], v[206:209], v[168:171], v[118:121]
	v_mfma_f32_16x16x32_bf16 v[110:113], v[216:219], v[168:171], v[110:113]
	v_mfma_f32_16x16x32_bf16 v[102:105], v[206:209], v[180:183], v[102:105]
	v_mfma_f32_16x16x32_bf16 v[94:97], v[216:219], v[180:183], v[94:97]
	v_mfma_f32_16x16x32_bf16 v[86:89], v[206:209], v[188:191], v[86:89]
	v_mfma_f32_16x16x32_bf16 v[78:81], v[216:219], v[188:191], v[78:81]
	v_mfma_f32_16x16x32_bf16 v[70:73], v[206:209], v[196:199], v[70:73]
	v_mfma_f32_16x16x32_bf16 v[66:69], v[216:219], v[196:199], v[66:69]
	v_mfma_f32_16x16x32_bf16 v[118:121], v[212:215], v[172:175], v[118:121]
	v_mfma_f32_16x16x32_bf16 v[110:113], v[220:223], v[172:175], v[110:113]
	v_mfma_f32_16x16x32_bf16 v[102:105], v[212:215], v[184:187], v[102:105]
	v_mfma_f32_16x16x32_bf16 v[94:97], v[220:223], v[184:187], v[94:97]
	v_mfma_f32_16x16x32_bf16 v[86:89], v[212:215], v[192:195], v[86:89]
	v_mfma_f32_16x16x32_bf16 v[78:81], v[220:223], v[192:195], v[78:81]
	v_mfma_f32_16x16x32_bf16 v[70:73], v[212:215], v[200:203], v[70:73]
	v_mfma_f32_16x16x32_bf16 v[66:69], v[220:223], v[200:203], v[66:69]
	s_barrier
	s_mov_b32 m0, s37
	ds_read_b128 v[168:171], v150 offset:49152
	ds_read_b128 v[172:175], v150 offset:50176
	ds_read_b128 v[180:183], v150 offset:51200
	ds_read_b128 v[184:187], v150 offset:52224
	ds_read_b128 v[188:191], v150 offset:53248
	ds_read_b128 v[192:195], v150 offset:54272
	ds_read_b128 v[196:199], v150 offset:55296
	ds_read_b128 v[200:203], v150 offset:56320
	global_load_lds_dwordx4 v130, s[100:101]
	s_mov_b32 m0, s38
	s_nop 0
	global_load_lds_dwordx4 v132, s[100:101]
	s_barrier
	s_waitcnt lgkmcnt(0)
	v_mfma_f32_16x16x32_bf16 v[62:65], v[152:155], v[168:171], v[62:65]
	v_mfma_f32_16x16x32_bf16 v[58:61], v[160:163], v[168:171], v[58:61]
	v_mfma_f32_16x16x32_bf16 v[50:53], v[152:155], v[180:183], v[50:53]
	v_mfma_f32_16x16x32_bf16 v[42:45], v[160:163], v[180:183], v[42:45]
	v_mfma_f32_16x16x32_bf16 v[34:37], v[152:155], v[188:191], v[34:37]
	v_mfma_f32_16x16x32_bf16 v[26:29], v[160:163], v[188:191], v[26:29]
	v_mfma_f32_16x16x32_bf16 v[18:21], v[152:155], v[196:199], v[18:21]
	v_mfma_f32_16x16x32_bf16 v[10:13], v[160:163], v[196:199], v[10:13]
	v_mfma_f32_16x16x32_bf16 v[62:65], v[156:159], v[172:175], v[62:65]
	v_mfma_f32_16x16x32_bf16 v[58:61], v[164:167], v[172:175], v[58:61]
	v_mfma_f32_16x16x32_bf16 v[50:53], v[156:159], v[184:187], v[50:53]
	v_mfma_f32_16x16x32_bf16 v[42:45], v[164:167], v[184:187], v[42:45]
	v_mfma_f32_16x16x32_bf16 v[34:37], v[156:159], v[192:195], v[34:37]
	v_mfma_f32_16x16x32_bf16 v[26:29], v[164:167], v[192:195], v[26:29]
	v_mfma_f32_16x16x32_bf16 v[18:21], v[156:159], v[200:203], v[18:21]
	v_mfma_f32_16x16x32_bf16 v[10:13], v[164:167], v[200:203], v[10:13]
	s_barrier
	s_add_u32 s18, s18, 0xb0080
	s_addc_u32 s19, s19, 0
	s_add_i32 s20, s20, s27
	s_mov_b32 m0, s20
	s_nop 0
	global_load_lds_dwordx4 v134, s[18:19]
	s_add_i32 m0, s20, 0x2000
	s_nop 0
	global_load_lds_dwordx4 v136, s[18:19]
	s_add_i32 s54, s54, 2
	s_add_u32 s16, s16, 0x100
	s_addc_u32 s17, s17, 0
	s_add_u32 s52, s52, 0x100
	s_addc_u32 s53, s53, 0
	s_cmp_gt_u32 s54, 41
	s_waitcnt vmcnt(6)
	s_barrier
	v_mfma_f32_16x16x32_bf16 v[54:57], v[206:209], v[168:171], v[54:57]
	v_mfma_f32_16x16x32_bf16 v[46:49], v[216:219], v[168:171], v[46:49]
	v_mfma_f32_16x16x32_bf16 v[38:41], v[206:209], v[180:183], v[38:41]
	v_mfma_f32_16x16x32_bf16 v[30:33], v[216:219], v[180:183], v[30:33]
	v_mfma_f32_16x16x32_bf16 v[22:25], v[206:209], v[188:191], v[22:25]
	v_mfma_f32_16x16x32_bf16 v[14:17], v[216:219], v[188:191], v[14:17]
	v_mfma_f32_16x16x32_bf16 v[6:9], v[206:209], v[196:199], v[6:9]
	v_mfma_f32_16x16x32_bf16 v[2:5], v[216:219], v[196:199], v[2:5]
	v_mfma_f32_16x16x32_bf16 v[54:57], v[212:215], v[172:175], v[54:57]
	v_mfma_f32_16x16x32_bf16 v[46:49], v[220:223], v[172:175], v[46:49]
	v_mfma_f32_16x16x32_bf16 v[38:41], v[212:215], v[184:187], v[38:41]
	v_mfma_f32_16x16x32_bf16 v[30:33], v[220:223], v[184:187], v[30:33]
	v_mfma_f32_16x16x32_bf16 v[22:25], v[212:215], v[192:195], v[22:25]
	v_mfma_f32_16x16x32_bf16 v[14:17], v[220:223], v[192:195], v[14:17]
	v_mfma_f32_16x16x32_bf16 v[6:9], v[212:215], v[200:203], v[6:9]
	v_mfma_f32_16x16x32_bf16 v[2:5], v[220:223], v[200:203], v[2:5]
	s_barrier
	s_cbranch_scc1 .Lpeel_p10_exit
.LBB0_1197:
	ds_read_b128 v[152:155], v149
	ds_read_b128 v[156:159], v149 offset:1024
	ds_read_b128 v[160:163], v149 offset:2048
	ds_read_b128 v[164:167], v149 offset:3072
	s_add_u32 s18, s16, 0xfff50080
	s_addc_u32 s19, s17, -1
	s_cmp_eq_u32 s54, 40
	s_cselect_b32 s21, s3, s19
	s_cselect_b32 s20, s2, s18
	s_cselect_b32 s19, s5, s53
	s_cselect_b32 s18, s4, s52
	s_add_i32 m0, s30, 0xc000
	ds_read_b128 v[168:171], v150
	ds_read_b128 v[172:175], v150 offset:1024
	ds_read_b128 v[180:183], v150 offset:2048
	ds_read_b128 v[184:187], v150 offset:3072
	ds_read_b128 v[188:191], v150 offset:4096
	ds_read_b128 v[192:195], v150 offset:5120
	ds_read_b128 v[196:199], v150 offset:6144
	ds_read_b128 v[200:203], v150 offset:7168
	global_load_lds_dwordx4 v138, s[16:17]
	s_add_i32 m0, s30, 0xe000
	s_nop 0
	global_load_lds_dwordx4 v140, s[16:17]
	s_waitcnt lgkmcnt(8)
	s_barrier
	s_waitcnt lgkmcnt(0)
	v_mfma_f32_16x16x32_bf16 v[126:129], v[152:155], v[168:171], v[126:129]
	v_mfma_f32_16x16x32_bf16 v[122:125], v[160:163], v[168:171], v[122:125]
	v_mfma_f32_16x16x32_bf16 v[114:117], v[152:155], v[180:183], v[114:117]
	v_mfma_f32_16x16x32_bf16 v[106:109], v[160:163], v[180:183], v[106:109]
	v_mfma_f32_16x16x32_bf16 v[98:101], v[152:155], v[188:191], v[98:101]
	v_mfma_f32_16x16x32_bf16 v[90:93], v[160:163], v[188:191], v[90:93]
	v_mfma_f32_16x16x32_bf16 v[82:85], v[152:155], v[196:199], v[82:85]
	v_mfma_f32_16x16x32_bf16 v[74:77], v[160:163], v[196:199], v[74:77]
	v_mfma_f32_16x16x32_bf16 v[126:129], v[156:159], v[172:175], v[126:129]
	v_mfma_f32_16x16x32_bf16 v[122:125], v[164:167], v[172:175], v[122:125]
	v_mfma_f32_16x16x32_bf16 v[114:117], v[156:159], v[184:187], v[114:117]
	v_mfma_f32_16x16x32_bf16 v[106:109], v[164:167], v[184:187], v[106:109]
	v_mfma_f32_16x16x32_bf16 v[98:101], v[156:159], v[192:195], v[98:101]
	v_mfma_f32_16x16x32_bf16 v[90:93], v[164:167], v[192:195], v[90:93]
	v_mfma_f32_16x16x32_bf16 v[82:85], v[156:159], v[200:203], v[82:85]
	v_mfma_f32_16x16x32_bf16 v[74:77], v[164:167], v[200:203], v[74:77]
	s_barrier
	s_add_i32 s55, s41, s27
	s_add_u32 s98, s18, 0x80
	s_addc_u32 s99, s19, 0
	s_mov_b32 m0, s55
	ds_read_b128 v[206:209], v151
	ds_read_b128 v[212:215], v151 offset:1024
	ds_read_b128 v[216:219], v151 offset:2048
	ds_read_b128 v[220:223], v151 offset:3072
	global_load_lds_dwordx4 v134, s[18:19]
	s_add_i32 m0, s55, 0x2000
	s_nop 0
	global_load_lds_dwordx4 v136, s[18:19]
	s_barrier
	s_waitcnt lgkmcnt(0)
	v_mfma_f32_16x16x32_bf16 v[118:121], v[206:209], v[168:171], v[118:121]
	v_mfma_f32_16x16x32_bf16 v[110:113], v[216:219], v[168:171], v[110:113]
	v_mfma_f32_16x16x32_bf16 v[102:105], v[206:209], v[180:183], v[102:105]
	v_mfma_f32_16x16x32_bf16 v[94:97], v[216:219], v[180:183], v[94:97]
	v_mfma_f32_16x16x32_bf16 v[86:89], v[206:209], v[188:191], v[86:89]
	v_mfma_f32_16x16x32_bf16 v[78:81], v[216:219], v[188:191], v[78:81]
	v_mfma_f32_16x16x32_bf16 v[70:73], v[206:209], v[196:199], v[70:73]
	v_mfma_f32_16x16x32_bf16 v[66:69], v[216:219], v[196:199], v[66:69]
	v_mfma_f32_16x16x32_bf16 v[118:121], v[212:215], v[172:175], v[118:121]
	v_mfma_f32_16x16x32_bf16 v[110:113], v[220:223], v[172:175], v[110:113]
	v_mfma_f32_16x16x32_bf16 v[102:105], v[212:215], v[184:187], v[102:105]
	v_mfma_f32_16x16x32_bf16 v[94:97], v[220:223], v[184:187], v[94:97]
	v_mfma_f32_16x16x32_bf16 v[86:89], v[212:215], v[192:195], v[86:89]
	v_mfma_f32_16x16x32_bf16 v[78:81], v[220:223], v[192:195], v[78:81]
	v_mfma_f32_16x16x32_bf16 v[70:73], v[212:215], v[200:203], v[70:73]
	v_mfma_f32_16x16x32_bf16 v[66:69], v[220:223], v[200:203], v[66:69]
	s_barrier
	s_mov_b32 m0, s30
	s_add_u32 s100, s20, 0x80
	s_addc_u32 s101, s21, 0
	ds_read_b128 v[168:171], v150 offset:16384
	ds_read_b128 v[172:175], v150 offset:17408
	ds_read_b128 v[180:183], v150 offset:18432
	ds_read_b128 v[184:187], v150 offset:19456
	ds_read_b128 v[188:191], v150 offset:20480
	ds_read_b128 v[192:195], v150 offset:21504
	ds_read_b128 v[196:199], v150 offset:22528
	ds_read_b128 v[200:203], v150 offset:23552
	global_load_lds_dwordx4 v130, s[20:21]
	s_mov_b32 m0, s31
	s_nop 0
	global_load_lds_dwordx4 v132, s[20:21]
	s_barrier
	s_waitcnt lgkmcnt(0)
	v_mfma_f32_16x16x32_bf16 v[62:65], v[152:155], v[168:171], v[62:65]
	v_mfma_f32_16x16x32_bf16 v[58:61], v[160:163], v[168:171], v[58:61]
	v_mfma_f32_16x16x32_bf16 v[50:53], v[152:155], v[180:183], v[50:53]
	v_mfma_f32_16x16x32_bf16 v[42:45], v[160:163], v[180:183], v[42:45]
	v_mfma_f32_16x16x32_bf16 v[34:37], v[152:155], v[188:191], v[34:37]
	v_mfma_f32_16x16x32_bf16 v[26:29], v[160:163], v[188:191], v[26:29]
	v_mfma_f32_16x16x32_bf16 v[18:21], v[152:155], v[196:199], v[18:21]
	v_mfma_f32_16x16x32_bf16 v[10:13], v[160:163], v[196:199], v[10:13]
	v_mfma_f32_16x16x32_bf16 v[62:65], v[156:159], v[172:175], v[62:65]
	v_mfma_f32_16x16x32_bf16 v[58:61], v[164:167], v[172:175], v[58:61]
	v_mfma_f32_16x16x32_bf16 v[50:53], v[156:159], v[184:187], v[50:53]
	v_mfma_f32_16x16x32_bf16 v[42:45], v[164:167], v[184:187], v[42:45]
	v_mfma_f32_16x16x32_bf16 v[34:37], v[156:159], v[192:195], v[34:37]
	v_mfma_f32_16x16x32_bf16 v[26:29], v[164:167], v[192:195], v[26:29]
	v_mfma_f32_16x16x32_bf16 v[18:21], v[156:159], v[200:203], v[18:21]
	v_mfma_f32_16x16x32_bf16 v[10:13], v[164:167], v[200:203], v[10:13]
	s_barrier
	s_add_u32 s56, s18, 0xb0000
	s_addc_u32 s57, s19, 0
	s_add_i32 s55, s42, s27
	s_mov_b32 m0, s55
	s_nop 0
	global_load_lds_dwordx4 v134, s[56:57]
	s_add_i32 m0, s55, 0x2000
	s_nop 0
	global_load_lds_dwordx4 v136, s[56:57]
	s_waitcnt vmcnt(6)
	s_barrier
	v_mfma_f32_16x16x32_bf16 v[54:57], v[206:209], v[168:171], v[54:57]
	v_mfma_f32_16x16x32_bf16 v[46:49], v[216:219], v[168:171], v[46:49]
	v_mfma_f32_16x16x32_bf16 v[38:41], v[206:209], v[180:183], v[38:41]
	v_mfma_f32_16x16x32_bf16 v[30:33], v[216:219], v[180:183], v[30:33]
	v_mfma_f32_16x16x32_bf16 v[22:25], v[206:209], v[188:191], v[22:25]
	v_mfma_f32_16x16x32_bf16 v[14:17], v[216:219], v[188:191], v[14:17]
	v_mfma_f32_16x16x32_bf16 v[6:9], v[206:209], v[196:199], v[6:9]
	v_mfma_f32_16x16x32_bf16 v[2:5], v[216:219], v[196:199], v[2:5]
	v_mfma_f32_16x16x32_bf16 v[54:57], v[212:215], v[172:175], v[54:57]
	v_mfma_f32_16x16x32_bf16 v[46:49], v[220:223], v[172:175], v[46:49]
	v_mfma_f32_16x16x32_bf16 v[38:41], v[212:215], v[184:187], v[38:41]
	v_mfma_f32_16x16x32_bf16 v[30:33], v[220:223], v[184:187], v[30:33]
	v_mfma_f32_16x16x32_bf16 v[22:25], v[212:215], v[192:195], v[22:25]
	v_mfma_f32_16x16x32_bf16 v[14:17], v[220:223], v[192:195], v[14:17]
	v_mfma_f32_16x16x32_bf16 v[6:9], v[212:215], v[200:203], v[6:9]
	v_mfma_f32_16x16x32_bf16 v[2:5], v[220:223], v[200:203], v[2:5]
	s_barrier
	s_add_i32 s55, 0, 0x18000
	v_add_u32_e32 v164, s55, v148
	ds_read_b128 v[152:155], v164
	ds_read_b128 v[156:159], v164 offset:1024
	ds_read_b128 v[160:163], v164 offset:2048
	ds_read_b128 v[164:167], v164 offset:3072
	s_add_u32 s20, s20, 0xb0000
	s_addc_u32 s21, s21, 0
	s_mov_b32 m0, s33
	ds_read_b128 v[168:171], v150 offset:32768
	ds_read_b128 v[172:175], v150 offset:33792
	ds_read_b128 v[180:183], v150 offset:34816
	ds_read_b128 v[184:187], v150 offset:35840
	ds_read_b128 v[188:191], v150 offset:36864
	ds_read_b128 v[192:195], v150 offset:37888
	ds_read_b128 v[196:199], v150 offset:38912
	ds_read_b128 v[200:203], v150 offset:39936
	global_load_lds_dwordx4 v130, s[20:21]
	s_mov_b32 m0, s34
	s_nop 0
	global_load_lds_dwordx4 v132, s[20:21]
	s_waitcnt lgkmcnt(8)
	s_barrier
	s_waitcnt lgkmcnt(0)
	v_mfma_f32_16x16x32_bf16 v[126:129], v[152:155], v[168:171], v[126:129]
	v_mfma_f32_16x16x32_bf16 v[122:125], v[160:163], v[168:171], v[122:125]
	v_mfma_f32_16x16x32_bf16 v[114:117], v[152:155], v[180:183], v[114:117]
	v_mfma_f32_16x16x32_bf16 v[106:109], v[160:163], v[180:183], v[106:109]
	v_mfma_f32_16x16x32_bf16 v[98:101], v[152:155], v[188:191], v[98:101]
	v_mfma_f32_16x16x32_bf16 v[90:93], v[160:163], v[188:191], v[90:93]
	v_mfma_f32_16x16x32_bf16 v[82:85], v[152:155], v[196:199], v[82:85]
	v_mfma_f32_16x16x32_bf16 v[74:77], v[160:163], v[196:199], v[74:77]
	v_mfma_f32_16x16x32_bf16 v[126:129], v[156:159], v[172:175], v[126:129]
	v_mfma_f32_16x16x32_bf16 v[122:125], v[164:167], v[172:175], v[122:125]
	v_mfma_f32_16x16x32_bf16 v[114:117], v[156:159], v[184:187], v[114:117]
	v_mfma_f32_16x16x32_bf16 v[106:109], v[164:167], v[184:187], v[106:109]
	v_mfma_f32_16x16x32_bf16 v[98:101], v[156:159], v[192:195], v[98:101]
	v_mfma_f32_16x16x32_bf16 v[90:93], v[164:167], v[192:195], v[90:93]
	v_mfma_f32_16x16x32_bf16 v[82:85], v[156:159], v[200:203], v[82:85]
	v_mfma_f32_16x16x32_bf16 v[74:77], v[164:167], v[200:203], v[74:77]
	s_barrier
	s_add_i32 s20, 0, 0x1c000
	s_add_i32 s21, s55, s27
	v_add_u32_e32 v179, s20, v148
	s_mov_b32 m0, s21
	ds_read_b128 v[206:209], v179
	ds_read_b128 v[212:215], v179 offset:1024
	ds_read_b128 v[216:219], v179 offset:2048
	ds_read_b128 v[220:223], v179 offset:3072
	global_load_lds_dwordx4 v134, s[98:99]
	s_add_i32 m0, s21, 0x2000
	s_nop 0
	global_load_lds_dwordx4 v136, s[98:99]
	s_barrier
	s_waitcnt lgkmcnt(0)
	v_mfma_f32_16x16x32_bf16 v[118:121], v[206:209], v[168:171], v[118:121]
	v_mfma_f32_16x16x32_bf16 v[110:113], v[216:219], v[168:171], v[110:113]
	v_mfma_f32_16x16x32_bf16 v[102:105], v[206:209], v[180:183], v[102:105]
	v_mfma_f32_16x16x32_bf16 v[94:97], v[216:219], v[180:183], v[94:97]
	v_mfma_f32_16x16x32_bf16 v[86:89], v[206:209], v[188:191], v[86:89]
	v_mfma_f32_16x16x32_bf16 v[78:81], v[216:219], v[188:191], v[78:81]
	v_mfma_f32_16x16x32_bf16 v[70:73], v[206:209], v[196:199], v[70:73]
	v_mfma_f32_16x16x32_bf16 v[66:69], v[216:219], v[196:199], v[66:69]
	v_mfma_f32_16x16x32_bf16 v[118:121], v[212:215], v[172:175], v[118:121]
	v_mfma_f32_16x16x32_bf16 v[110:113], v[220:223], v[172:175], v[110:113]
	v_mfma_f32_16x16x32_bf16 v[102:105], v[212:215], v[184:187], v[102:105]
	v_mfma_f32_16x16x32_bf16 v[94:97], v[220:223], v[184:187], v[94:97]
	v_mfma_f32_16x16x32_bf16 v[86:89], v[212:215], v[192:195], v[86:89]
	v_mfma_f32_16x16x32_bf16 v[78:81], v[220:223], v[192:195], v[78:81]
	v_mfma_f32_16x16x32_bf16 v[70:73], v[212:215], v[200:203], v[70:73]
	v_mfma_f32_16x16x32_bf16 v[66:69], v[220:223], v[200:203], v[66:69]
	s_barrier
	s_mov_b32 m0, s37
	ds_read_b128 v[168:171], v150 offset:49152
	ds_read_b128 v[172:175], v150 offset:50176
	ds_read_b128 v[180:183], v150 offset:51200
	ds_read_b128 v[184:187], v150 offset:52224
	ds_read_b128 v[188:191], v150 offset:53248
	ds_read_b128 v[192:195], v150 offset:54272
	ds_read_b128 v[196:199], v150 offset:55296
	ds_read_b128 v[200:203], v150 offset:56320
	global_load_lds_dwordx4 v130, s[100:101]
	s_mov_b32 m0, s38
	s_nop 0
	global_load_lds_dwordx4 v132, s[100:101]
	s_barrier
	s_waitcnt lgkmcnt(0)
	v_mfma_f32_16x16x32_bf16 v[62:65], v[152:155], v[168:171], v[62:65]
	v_mfma_f32_16x16x32_bf16 v[58:61], v[160:163], v[168:171], v[58:61]
	v_mfma_f32_16x16x32_bf16 v[50:53], v[152:155], v[180:183], v[50:53]
	v_mfma_f32_16x16x32_bf16 v[42:45], v[160:163], v[180:183], v[42:45]
	v_mfma_f32_16x16x32_bf16 v[34:37], v[152:155], v[188:191], v[34:37]
	v_mfma_f32_16x16x32_bf16 v[26:29], v[160:163], v[188:191], v[26:29]
	v_mfma_f32_16x16x32_bf16 v[18:21], v[152:155], v[196:199], v[18:21]
	v_mfma_f32_16x16x32_bf16 v[10:13], v[160:163], v[196:199], v[10:13]
	v_mfma_f32_16x16x32_bf16 v[62:65], v[156:159], v[172:175], v[62:65]
	v_mfma_f32_16x16x32_bf16 v[58:61], v[164:167], v[172:175], v[58:61]
	v_mfma_f32_16x16x32_bf16 v[50:53], v[156:159], v[184:187], v[50:53]
	v_mfma_f32_16x16x32_bf16 v[42:45], v[164:167], v[184:187], v[42:45]
	v_mfma_f32_16x16x32_bf16 v[34:37], v[156:159], v[192:195], v[34:37]
	v_mfma_f32_16x16x32_bf16 v[26:29], v[164:167], v[192:195], v[26:29]
	v_mfma_f32_16x16x32_bf16 v[18:21], v[156:159], v[200:203], v[18:21]
	v_mfma_f32_16x16x32_bf16 v[10:13], v[164:167], v[200:203], v[10:13]
	s_barrier
	s_add_u32 s18, s18, 0xb0080
	s_addc_u32 s19, s19, 0
	s_add_i32 s20, s20, s27
	s_mov_b32 m0, s20
	s_nop 0
	global_load_lds_dwordx4 v134, s[18:19]
	s_add_i32 m0, s20, 0x2000
	s_nop 0
	global_load_lds_dwordx4 v136, s[18:19]
	s_add_i32 s54, s54, 2
	s_add_u32 s16, s16, 0x100
	s_addc_u32 s17, s17, 0
	s_add_u32 s52, s52, 0x100
	s_addc_u32 s53, s53, 0
	s_cmp_gt_u32 s54, 41
	s_waitcnt vmcnt(6)
	s_barrier
	v_mfma_f32_16x16x32_bf16 v[54:57], v[206:209], v[168:171], v[54:57]
	v_mfma_f32_16x16x32_bf16 v[46:49], v[216:219], v[168:171], v[46:49]
	v_mfma_f32_16x16x32_bf16 v[38:41], v[206:209], v[180:183], v[38:41]
	v_mfma_f32_16x16x32_bf16 v[30:33], v[216:219], v[180:183], v[30:33]
	v_mfma_f32_16x16x32_bf16 v[22:25], v[206:209], v[188:191], v[22:25]
	v_mfma_f32_16x16x32_bf16 v[14:17], v[216:219], v[188:191], v[14:17]
	v_mfma_f32_16x16x32_bf16 v[6:9], v[206:209], v[196:199], v[6:9]
	v_mfma_f32_16x16x32_bf16 v[2:5], v[216:219], v[196:199], v[2:5]
	v_mfma_f32_16x16x32_bf16 v[54:57], v[212:215], v[172:175], v[54:57]
	v_mfma_f32_16x16x32_bf16 v[46:49], v[220:223], v[172:175], v[46:49]
	v_mfma_f32_16x16x32_bf16 v[38:41], v[212:215], v[184:187], v[38:41]
	v_mfma_f32_16x16x32_bf16 v[30:33], v[220:223], v[184:187], v[30:33]
	v_mfma_f32_16x16x32_bf16 v[22:25], v[212:215], v[192:195], v[22:25]
	v_mfma_f32_16x16x32_bf16 v[14:17], v[220:223], v[192:195], v[14:17]
	v_mfma_f32_16x16x32_bf16 v[6:9], v[212:215], v[200:203], v[6:9]
	v_mfma_f32_16x16x32_bf16 v[2:5], v[220:223], v[200:203], v[2:5]
	s_barrier
	s_cbranch_scc0 .LBB0_1197
